# six GEMM K-loops: loop-carried pointer/counter SALU updates moved from after the last barrier into the last MFMAs of phase 4 (loop-edge edit)
# speedup vs baseline: 1.0067x; 1.0062x over previous
.LBB0_221:
	s_add_u32 s42, s38, 0xfffc0080
	s_addc_u32 s43, s39, -1
	s_add_i32 s61, 0, 0x10000
	s_cmp_eq_u32 s59, 12
	s_cselect_b32 s45, s11, s43
	s_cselect_b32 s44, s13, s42
	s_cselect_b32 s43, s55, s58
	s_cselect_b32 s42, s56, s57
	s_add_i32 s64, 0, 0x14000
	v_add_u32_e32 v156, s61, v150
	v_add_u32_e32 v172, s64, v150
	ds_read_b128 v[140:143], v156
	ds_read_b128 v[144:147], v156 offset:1024
	ds_read_b128 v[152:155], v156 offset:2048
	ds_read_b128 v[156:159], v156 offset:3072
	ds_read_b128 v[160:163], v172
	ds_read_b128 v[164:167], v172 offset:1024
	ds_read_b128 v[168:171], v172 offset:2048
	ds_read_b128 v[172:175], v172 offset:3072
	v_lshl_add_u64 v[218:219], s[38:39], 0, v[138:139]
	s_add_i32 m0, s33, 0xc000
	ds_read_b128 v[176:179], v151
	ds_read_b128 v[180:183], v151 offset:1024
	ds_read_b128 v[184:187], v151 offset:2048
	ds_read_b128 v[188:191], v151 offset:3072
	ds_read_b128 v[194:197], v151 offset:4096
	ds_read_b128 v[198:201], v151 offset:5120
	ds_read_b128 v[202:205], v151 offset:6144
	ds_read_b128 v[214:217], v151 offset:7168
	global_load_lds_dwordx4 v[218:219], off
	v_lshl_add_u64 v[218:219], s[38:39], 0, v[136:137]
	s_add_i32 m0, s33, 0xe000
	s_nop 0
	global_load_lds_dwordx4 v[218:219], off
	s_waitcnt vmcnt(8)
	s_waitcnt lgkmcnt(0)
	s_barrier
	s_setprio 1
	s_waitcnt lgkmcnt(0)
	v_mfma_f32_16x16x32_bf16 v[124:127], v[140:143], v[176:179], v[124:127]
	v_mfma_f32_16x16x32_bf16 v[120:123], v[152:155], v[176:179], v[120:123]
	v_mfma_f32_16x16x32_bf16 v[108:111], v[140:143], v[184:187], v[108:111]
	v_mfma_f32_16x16x32_bf16 v[104:107], v[152:155], v[184:187], v[104:107]
	v_mfma_f32_16x16x32_bf16 v[92:95], v[140:143], v[194:197], v[92:95]
	v_mfma_f32_16x16x32_bf16 v[88:91], v[152:155], v[194:197], v[88:91]
	v_mfma_f32_16x16x32_bf16 v[76:79], v[140:143], v[202:205], v[76:79]
	v_mfma_f32_16x16x32_bf16 v[72:75], v[152:155], v[202:205], v[72:75]
	v_mfma_f32_16x16x32_bf16 v[124:127], v[144:147], v[180:183], v[124:127]
	v_mfma_f32_16x16x32_bf16 v[120:123], v[156:159], v[180:183], v[120:123]
	v_mfma_f32_16x16x32_bf16 v[108:111], v[144:147], v[188:191], v[108:111]
	v_mfma_f32_16x16x32_bf16 v[104:107], v[156:159], v[188:191], v[104:107]
	v_mfma_f32_16x16x32_bf16 v[92:95], v[144:147], v[198:201], v[92:95]
	v_mfma_f32_16x16x32_bf16 v[88:91], v[156:159], v[198:201], v[88:91]
	v_mfma_f32_16x16x32_bf16 v[76:79], v[144:147], v[214:217], v[76:79]
	v_mfma_f32_16x16x32_bf16 v[72:75], v[156:159], v[214:217], v[72:75]
	s_setprio 0
	s_setprio 1
	v_mfma_f32_16x16x32_bf16 v[116:119], v[160:163], v[176:179], v[116:119]
	v_mfma_f32_16x16x32_bf16 v[112:115], v[168:171], v[176:179], v[112:115]
	v_mfma_f32_16x16x32_bf16 v[100:103], v[160:163], v[184:187], v[100:103]
	v_mfma_f32_16x16x32_bf16 v[96:99], v[168:171], v[184:187], v[96:99]
	v_mfma_f32_16x16x32_bf16 v[84:87], v[160:163], v[194:197], v[84:87]
	v_mfma_f32_16x16x32_bf16 v[80:83], v[168:171], v[194:197], v[80:83]
	v_mfma_f32_16x16x32_bf16 v[68:71], v[160:163], v[202:205], v[68:71]
	v_mfma_f32_16x16x32_bf16 v[64:67], v[168:171], v[202:205], v[64:67]
	v_mfma_f32_16x16x32_bf16 v[116:119], v[164:167], v[180:183], v[116:119]
	v_mfma_f32_16x16x32_bf16 v[112:115], v[172:175], v[180:183], v[112:115]
	v_mfma_f32_16x16x32_bf16 v[100:103], v[164:167], v[188:191], v[100:103]
	v_mfma_f32_16x16x32_bf16 v[96:99], v[172:175], v[188:191], v[96:99]
	v_mfma_f32_16x16x32_bf16 v[84:87], v[164:167], v[198:201], v[84:87]
	v_mfma_f32_16x16x32_bf16 v[80:83], v[172:175], v[198:201], v[80:83]
	v_mfma_f32_16x16x32_bf16 v[68:71], v[164:167], v[214:217], v[68:71]
	v_mfma_f32_16x16x32_bf16 v[64:67], v[172:175], v[214:217], v[64:67]
	s_setprio 0
	s_barrier
	s_add_i32 s61, s61, s27
	v_lshl_add_u64 v[218:219], s[42:43], 0, v[132:133]
	s_mov_b32 m0, s61
	ds_read_b128 v[176:179], v151 offset:16384
	ds_read_b128 v[180:183], v151 offset:17408
	ds_read_b128 v[184:187], v151 offset:18432
	ds_read_b128 v[188:191], v151 offset:19456
	ds_read_b128 v[194:197], v151 offset:20480
	ds_read_b128 v[198:201], v151 offset:21504
	ds_read_b128 v[202:205], v151 offset:22528
	ds_read_b128 v[214:217], v151 offset:23552
	global_load_lds_dwordx4 v[218:219], off
	s_add_i32 m0, s61, 0x2000
	s_add_u32 s62, s42, 0x40000
	v_lshl_add_u64 v[220:221], s[42:43], 0, v[128:129]
	s_addc_u32 s63, s43, 0
	s_add_i32 s61, s64, s27
	global_load_lds_dwordx4 v[220:221], off
	v_lshl_add_u64 v[222:223], s[62:63], 0, v[132:133]
	s_mov_b32 m0, s61
	v_lshl_add_u64 v[224:225], s[44:45], 0, v[130:131]
	global_load_lds_dwordx4 v[222:223], off
	v_lshl_add_u64 v[222:223], s[62:63], 0, v[128:129]
	s_add_i32 m0, s61, 0x2000
	s_nop 0
	global_load_lds_dwordx4 v[222:223], off
	v_lshl_add_u64 v[222:223], s[44:45], 0, v[134:135]
	s_mov_b32 m0, s33
	s_nop 0
	global_load_lds_dwordx4 v[222:223], off
	s_mov_b32 m0, s40
	s_nop 0
	global_load_lds_dwordx4 v[224:225], off
	s_waitcnt vmcnt(8)
	s_waitcnt lgkmcnt(0)
	s_barrier
	s_setprio 1
	s_waitcnt lgkmcnt(0)
	v_mfma_f32_16x16x32_bf16 v[60:63], v[140:143], v[176:179], v[60:63]
	v_mfma_f32_16x16x32_bf16 v[56:59], v[152:155], v[176:179], v[56:59]
	v_mfma_f32_16x16x32_bf16 v[44:47], v[140:143], v[184:187], v[44:47]
	v_mfma_f32_16x16x32_bf16 v[40:43], v[152:155], v[184:187], v[40:43]
	v_mfma_f32_16x16x32_bf16 v[28:31], v[140:143], v[194:197], v[28:31]
	v_mfma_f32_16x16x32_bf16 v[24:27], v[152:155], v[194:197], v[24:27]
	v_mfma_f32_16x16x32_bf16 v[12:15], v[140:143], v[202:205], v[12:15]
	v_mfma_f32_16x16x32_bf16 v[8:11], v[152:155], v[202:205], v[8:11]
	v_mfma_f32_16x16x32_bf16 v[60:63], v[144:147], v[180:183], v[60:63]
	v_mfma_f32_16x16x32_bf16 v[56:59], v[156:159], v[180:183], v[56:59]
	v_mfma_f32_16x16x32_bf16 v[44:47], v[144:147], v[188:191], v[44:47]
	v_mfma_f32_16x16x32_bf16 v[40:43], v[156:159], v[188:191], v[40:43]
	v_mfma_f32_16x16x32_bf16 v[28:31], v[144:147], v[198:201], v[28:31]
	v_mfma_f32_16x16x32_bf16 v[24:27], v[156:159], v[198:201], v[24:27]
	v_mfma_f32_16x16x32_bf16 v[12:15], v[144:147], v[214:217], v[12:15]
	v_mfma_f32_16x16x32_bf16 v[8:11], v[156:159], v[214:217], v[8:11]
	s_setprio 0
	s_setprio 1
	v_mfma_f32_16x16x32_bf16 v[52:55], v[160:163], v[176:179], v[52:55]
	v_mfma_f32_16x16x32_bf16 v[48:51], v[168:171], v[176:179], v[48:51]
	v_mfma_f32_16x16x32_bf16 v[36:39], v[160:163], v[184:187], v[36:39]
	v_mfma_f32_16x16x32_bf16 v[32:35], v[168:171], v[184:187], v[32:35]
	v_mfma_f32_16x16x32_bf16 v[20:23], v[160:163], v[194:197], v[20:23]
	v_mfma_f32_16x16x32_bf16 v[16:19], v[168:171], v[194:197], v[16:19]
	v_mfma_f32_16x16x32_bf16 v[4:7], v[160:163], v[202:205], v[4:7]
	v_mfma_f32_16x16x32_bf16 v[0:3], v[168:171], v[202:205], v[0:3]
	v_mfma_f32_16x16x32_bf16 v[52:55], v[164:167], v[180:183], v[52:55]
	v_mfma_f32_16x16x32_bf16 v[48:51], v[172:175], v[180:183], v[48:51]
	v_mfma_f32_16x16x32_bf16 v[36:39], v[164:167], v[188:191], v[36:39]
	v_mfma_f32_16x16x32_bf16 v[32:35], v[172:175], v[188:191], v[32:35]
	v_mfma_f32_16x16x32_bf16 v[20:23], v[164:167], v[198:201], v[20:23]
	v_mfma_f32_16x16x32_bf16 v[16:19], v[172:175], v[198:201], v[16:19]
	v_mfma_f32_16x16x32_bf16 v[4:7], v[164:167], v[214:217], v[4:7]
	v_mfma_f32_16x16x32_bf16 v[0:3], v[172:175], v[214:217], v[0:3]
	s_setprio 0
	s_barrier
	s_add_i32 s61, 0, 0x18000
	s_add_i32 s62, 0, 0x1c000
	v_add_u32_e32 v156, s61, v150
	v_add_u32_e32 v172, s62, v150
	ds_read_b128 v[140:143], v156
	ds_read_b128 v[144:147], v156 offset:1024
	ds_read_b128 v[152:155], v156 offset:2048
	ds_read_b128 v[156:159], v156 offset:3072
	ds_read_b128 v[160:163], v172
	ds_read_b128 v[164:167], v172 offset:1024
	ds_read_b128 v[168:171], v172 offset:2048
	ds_read_b128 v[172:175], v172 offset:3072
	s_add_u32 s44, s44, 0x40000
	s_addc_u32 s45, s45, 0
	s_mov_b32 m0, s46
	v_lshl_add_u64 v[226:227], s[44:45], 0, v[134:135]
	ds_read_b128 v[176:179], v151 offset:32768
	ds_read_b128 v[180:183], v151 offset:33792
	ds_read_b128 v[184:187], v151 offset:34816
	ds_read_b128 v[188:191], v151 offset:35840
	ds_read_b128 v[194:197], v151 offset:36864
	ds_read_b128 v[198:201], v151 offset:37888
	ds_read_b128 v[202:205], v151 offset:38912
	ds_read_b128 v[214:217], v151 offset:39936
	global_load_lds_dwordx4 v[226:227], off
	v_lshl_add_u64 v[226:227], s[44:45], 0, v[130:131]
	s_mov_b32 m0, s47
	s_nop 0
	global_load_lds_dwordx4 v[226:227], off
	s_waitcnt vmcnt(8)
	s_waitcnt lgkmcnt(0)
	s_barrier
	s_setprio 1
	s_waitcnt lgkmcnt(0)
	v_mfma_f32_16x16x32_bf16 v[124:127], v[140:143], v[176:179], v[124:127]
	v_mfma_f32_16x16x32_bf16 v[120:123], v[152:155], v[176:179], v[120:123]
	v_mfma_f32_16x16x32_bf16 v[108:111], v[140:143], v[184:187], v[108:111]
	v_mfma_f32_16x16x32_bf16 v[104:107], v[152:155], v[184:187], v[104:107]
	v_mfma_f32_16x16x32_bf16 v[92:95], v[140:143], v[194:197], v[92:95]
	v_mfma_f32_16x16x32_bf16 v[88:91], v[152:155], v[194:197], v[88:91]
	v_mfma_f32_16x16x32_bf16 v[76:79], v[140:143], v[202:205], v[76:79]
	v_mfma_f32_16x16x32_bf16 v[72:75], v[152:155], v[202:205], v[72:75]
	v_mfma_f32_16x16x32_bf16 v[124:127], v[144:147], v[180:183], v[124:127]
	v_mfma_f32_16x16x32_bf16 v[120:123], v[156:159], v[180:183], v[120:123]
	v_mfma_f32_16x16x32_bf16 v[108:111], v[144:147], v[188:191], v[108:111]
	v_mfma_f32_16x16x32_bf16 v[104:107], v[156:159], v[188:191], v[104:107]
	v_mfma_f32_16x16x32_bf16 v[92:95], v[144:147], v[198:201], v[92:95]
	v_mfma_f32_16x16x32_bf16 v[88:91], v[156:159], v[198:201], v[88:91]
	v_mfma_f32_16x16x32_bf16 v[76:79], v[144:147], v[214:217], v[76:79]
	v_mfma_f32_16x16x32_bf16 v[72:75], v[156:159], v[214:217], v[72:75]
	s_setprio 0
	s_setprio 1
	v_mfma_f32_16x16x32_bf16 v[116:119], v[160:163], v[176:179], v[116:119]
	v_mfma_f32_16x16x32_bf16 v[112:115], v[168:171], v[176:179], v[112:115]
	v_mfma_f32_16x16x32_bf16 v[100:103], v[160:163], v[184:187], v[100:103]
	v_mfma_f32_16x16x32_bf16 v[96:99], v[168:171], v[184:187], v[96:99]
	v_mfma_f32_16x16x32_bf16 v[84:87], v[160:163], v[194:197], v[84:87]
	v_mfma_f32_16x16x32_bf16 v[80:83], v[168:171], v[194:197], v[80:83]
	v_mfma_f32_16x16x32_bf16 v[68:71], v[160:163], v[202:205], v[68:71]
	v_mfma_f32_16x16x32_bf16 v[64:67], v[168:171], v[202:205], v[64:67]
	v_mfma_f32_16x16x32_bf16 v[116:119], v[164:167], v[180:183], v[116:119]
	v_mfma_f32_16x16x32_bf16 v[112:115], v[172:175], v[180:183], v[112:115]
	v_mfma_f32_16x16x32_bf16 v[100:103], v[164:167], v[188:191], v[100:103]
	v_mfma_f32_16x16x32_bf16 v[96:99], v[172:175], v[188:191], v[96:99]
	v_mfma_f32_16x16x32_bf16 v[84:87], v[164:167], v[198:201], v[84:87]
	v_mfma_f32_16x16x32_bf16 v[80:83], v[172:175], v[198:201], v[80:83]
	v_mfma_f32_16x16x32_bf16 v[68:71], v[164:167], v[214:217], v[68:71]
	v_mfma_f32_16x16x32_bf16 v[64:67], v[172:175], v[214:217], v[64:67]
	s_setprio 0
	s_barrier
	s_add_i32 s44, s61, s27
	v_lshl_add_u64 v[218:219], v[218:219], 0, s[76:77]
	s_mov_b32 m0, s44
	ds_read_b128 v[176:179], v151 offset:49152
	ds_read_b128 v[180:183], v151 offset:50176
	ds_read_b128 v[184:187], v151 offset:51200
	ds_read_b128 v[188:191], v151 offset:52224
	ds_read_b128 v[194:197], v151 offset:53248
	ds_read_b128 v[198:201], v151 offset:54272
	ds_read_b128 v[202:205], v151 offset:55296
	ds_read_b128 v[214:217], v151 offset:56320
	global_load_lds_dwordx4 v[218:219], off
	s_add_i32 m0, s44, 0x2000
	s_add_u32 s42, s42, 0x40080
	v_lshl_add_u64 v[218:219], v[220:221], 0, s[76:77]
	s_addc_u32 s43, s43, 0
	s_add_i32 s44, s62, s27
	global_load_lds_dwordx4 v[218:219], off
	v_lshl_add_u64 v[218:219], s[42:43], 0, v[132:133]
	s_mov_b32 m0, s44
	s_nop 0
	global_load_lds_dwordx4 v[218:219], off
	v_lshl_add_u64 v[218:219], s[42:43], 0, v[128:129]
	s_add_i32 m0, s44, 0x2000
	s_nop 0
	global_load_lds_dwordx4 v[218:219], off
	v_lshl_add_u64 v[218:219], v[222:223], 0, s[76:77]
	s_mov_b32 m0, s52
	s_nop 0
	global_load_lds_dwordx4 v[218:219], off
	v_lshl_add_u64 v[218:219], v[224:225], 0, s[76:77]
	s_mov_b32 m0, s53
	s_nop 0
	global_load_lds_dwordx4 v[218:219], off
	s_waitcnt vmcnt(8)
	s_waitcnt lgkmcnt(0)
	s_barrier
	s_setprio 1
	s_waitcnt lgkmcnt(0)
	v_mfma_f32_16x16x32_bf16 v[60:63], v[140:143], v[176:179], v[60:63]
	v_mfma_f32_16x16x32_bf16 v[56:59], v[152:155], v[176:179], v[56:59]
	v_mfma_f32_16x16x32_bf16 v[44:47], v[140:143], v[184:187], v[44:47]
	v_mfma_f32_16x16x32_bf16 v[40:43], v[152:155], v[184:187], v[40:43]
	v_mfma_f32_16x16x32_bf16 v[28:31], v[140:143], v[194:197], v[28:31]
	v_mfma_f32_16x16x32_bf16 v[24:27], v[152:155], v[194:197], v[24:27]
	v_mfma_f32_16x16x32_bf16 v[12:15], v[140:143], v[202:205], v[12:15]
	v_mfma_f32_16x16x32_bf16 v[8:11], v[152:155], v[202:205], v[8:11]
	v_mfma_f32_16x16x32_bf16 v[60:63], v[144:147], v[180:183], v[60:63]
	v_mfma_f32_16x16x32_bf16 v[56:59], v[156:159], v[180:183], v[56:59]
	v_mfma_f32_16x16x32_bf16 v[44:47], v[144:147], v[188:191], v[44:47]
	v_mfma_f32_16x16x32_bf16 v[40:43], v[156:159], v[188:191], v[40:43]
	v_mfma_f32_16x16x32_bf16 v[28:31], v[144:147], v[198:201], v[28:31]
	v_mfma_f32_16x16x32_bf16 v[24:27], v[156:159], v[198:201], v[24:27]
	v_mfma_f32_16x16x32_bf16 v[12:15], v[144:147], v[214:217], v[12:15]
	v_mfma_f32_16x16x32_bf16 v[8:11], v[156:159], v[214:217], v[8:11]
	s_setprio 0
	s_setprio 1
	v_mfma_f32_16x16x32_bf16 v[52:55], v[160:163], v[176:179], v[52:55]
	v_mfma_f32_16x16x32_bf16 v[48:51], v[168:171], v[176:179], v[48:51]
	v_mfma_f32_16x16x32_bf16 v[36:39], v[160:163], v[184:187], v[36:39]
	v_mfma_f32_16x16x32_bf16 v[32:35], v[168:171], v[184:187], v[32:35]
	v_mfma_f32_16x16x32_bf16 v[20:23], v[160:163], v[194:197], v[20:23]
	v_mfma_f32_16x16x32_bf16 v[16:19], v[168:171], v[194:197], v[16:19]
	v_mfma_f32_16x16x32_bf16 v[4:7], v[160:163], v[202:205], v[4:7]
	v_mfma_f32_16x16x32_bf16 v[0:3], v[168:171], v[202:205], v[0:3]
	v_mfma_f32_16x16x32_bf16 v[52:55], v[164:167], v[180:183], v[52:55]
	v_mfma_f32_16x16x32_bf16 v[48:51], v[172:175], v[180:183], v[48:51]
	v_mfma_f32_16x16x32_bf16 v[36:39], v[164:167], v[188:191], v[36:39]
	v_mfma_f32_16x16x32_bf16 v[32:35], v[172:175], v[188:191], v[32:35]
	s_add_i32 s59, s59, 2
	s_add_u32 s57, s57, 0x100
	s_addc_u32 s58, s58, 0
	s_add_u32 s38, s38, 0x100
	s_addc_u32 s39, s39, 0
	v_mfma_f32_16x16x32_bf16 v[20:23], v[164:167], v[198:201], v[20:23]
	v_mfma_f32_16x16x32_bf16 v[16:19], v[172:175], v[198:201], v[16:19]
	v_mfma_f32_16x16x32_bf16 v[4:7], v[164:167], v[214:217], v[4:7]
	v_mfma_f32_16x16x32_bf16 v[0:3], v[172:175], v[214:217], v[0:3]
	s_setprio 0
	s_barrier
	s_cmp_gt_u32 s59, 13
	s_cbranch_scc0 .LBB0_221
	s_and_b64 vcc, exec, s[8:9]
	s_cbranch_vccz .LBB0_224
	s_barrier

.LBB0_299:
	s_add_u32 s14, s12, 0xfffc0080
	s_addc_u32 s15, s13, -1
	s_add_i32 s40, 0, 0x10000
	s_cmp_eq_u32 s39, 12
	s_cselect_b32 s17, s9, s15
	s_cselect_b32 s16, s11, s14
	s_cselect_b32 s15, s30, s38
	s_cselect_b32 s14, s31, s33
	s_add_i32 s52, 0, 0x14000
	v_add_u32_e32 v140, s40, v178
	v_add_u32_e32 v168, s52, v178
	ds_read_b128 v[128:131], v140
	ds_read_b128 v[132:135], v140 offset:1024
	ds_read_b128 v[136:139], v140 offset:2048
	ds_read_b128 v[140:143], v140 offset:3072
	ds_read_b128 v[156:159], v168
	ds_read_b128 v[160:163], v168 offset:1024
	ds_read_b128 v[164:167], v168 offset:2048
	ds_read_b128 v[168:171], v168 offset:3072
	v_lshl_add_u64 v[218:219], s[12:13], 0, v[154:155]
	s_add_i32 m0, s48, 0xc000
	ds_read_b128 v[172:175], v179
	ds_read_b128 v[180:183], v179 offset:1024
	ds_read_b128 v[184:187], v179 offset:2048
	ds_read_b128 v[188:191], v179 offset:3072
	ds_read_b128 v[194:197], v179 offset:4096
	ds_read_b128 v[198:201], v179 offset:5120
	ds_read_b128 v[202:205], v179 offset:6144
	ds_read_b128 v[214:217], v179 offset:7168
	global_load_lds_dwordx4 v[218:219], off
	v_lshl_add_u64 v[218:219], s[12:13], 0, v[152:153]
	s_add_i32 m0, s48, 0xe000
	s_nop 0
	global_load_lds_dwordx4 v[218:219], off
	s_waitcnt vmcnt(8)
	s_waitcnt lgkmcnt(0)
	s_barrier
	s_setprio 1
	s_waitcnt lgkmcnt(0)
	v_mfma_f32_16x16x32_bf16 v[124:127], v[128:131], v[172:175], v[124:127]
	v_mfma_f32_16x16x32_bf16 v[120:123], v[136:139], v[172:175], v[120:123]
	v_mfma_f32_16x16x32_bf16 v[108:111], v[128:131], v[184:187], v[108:111]
	v_mfma_f32_16x16x32_bf16 v[104:107], v[136:139], v[184:187], v[104:107]
	v_mfma_f32_16x16x32_bf16 v[92:95], v[128:131], v[194:197], v[92:95]
	v_mfma_f32_16x16x32_bf16 v[88:91], v[136:139], v[194:197], v[88:91]
	v_mfma_f32_16x16x32_bf16 v[76:79], v[128:131], v[202:205], v[76:79]
	v_mfma_f32_16x16x32_bf16 v[72:75], v[136:139], v[202:205], v[72:75]
	v_mfma_f32_16x16x32_bf16 v[124:127], v[132:135], v[180:183], v[124:127]
	v_mfma_f32_16x16x32_bf16 v[120:123], v[140:143], v[180:183], v[120:123]
	v_mfma_f32_16x16x32_bf16 v[108:111], v[132:135], v[188:191], v[108:111]
	v_mfma_f32_16x16x32_bf16 v[104:107], v[140:143], v[188:191], v[104:107]
	v_mfma_f32_16x16x32_bf16 v[92:95], v[132:135], v[198:201], v[92:95]
	v_mfma_f32_16x16x32_bf16 v[88:91], v[140:143], v[198:201], v[88:91]
	v_mfma_f32_16x16x32_bf16 v[76:79], v[132:135], v[214:217], v[76:79]
	v_mfma_f32_16x16x32_bf16 v[72:75], v[140:143], v[214:217], v[72:75]
	s_setprio 0
	s_setprio 1
	v_mfma_f32_16x16x32_bf16 v[116:119], v[156:159], v[172:175], v[116:119]
	v_mfma_f32_16x16x32_bf16 v[112:115], v[164:167], v[172:175], v[112:115]
	v_mfma_f32_16x16x32_bf16 v[100:103], v[156:159], v[184:187], v[100:103]
	v_mfma_f32_16x16x32_bf16 v[96:99], v[164:167], v[184:187], v[96:99]
	v_mfma_f32_16x16x32_bf16 v[84:87], v[156:159], v[194:197], v[84:87]
	v_mfma_f32_16x16x32_bf16 v[80:83], v[164:167], v[194:197], v[80:83]
	v_mfma_f32_16x16x32_bf16 v[68:71], v[156:159], v[202:205], v[68:71]
	v_mfma_f32_16x16x32_bf16 v[64:67], v[164:167], v[202:205], v[64:67]
	v_mfma_f32_16x16x32_bf16 v[116:119], v[160:163], v[180:183], v[116:119]
	v_mfma_f32_16x16x32_bf16 v[112:115], v[168:171], v[180:183], v[112:115]
	v_mfma_f32_16x16x32_bf16 v[100:103], v[160:163], v[188:191], v[100:103]
	v_mfma_f32_16x16x32_bf16 v[96:99], v[168:171], v[188:191], v[96:99]
	v_mfma_f32_16x16x32_bf16 v[84:87], v[160:163], v[198:201], v[84:87]
	v_mfma_f32_16x16x32_bf16 v[80:83], v[168:171], v[198:201], v[80:83]
	v_mfma_f32_16x16x32_bf16 v[68:71], v[160:163], v[214:217], v[68:71]
	v_mfma_f32_16x16x32_bf16 v[64:67], v[168:171], v[214:217], v[64:67]
	s_setprio 0
	s_barrier
	s_add_i32 s40, s40, s61
	v_lshl_add_u64 v[218:219], s[14:15], 0, v[148:149]
	s_mov_b32 m0, s40
	ds_read_b128 v[172:175], v179 offset:16384
	ds_read_b128 v[180:183], v179 offset:17408
	ds_read_b128 v[184:187], v179 offset:18432
	ds_read_b128 v[188:191], v179 offset:19456
	ds_read_b128 v[194:197], v179 offset:20480
	ds_read_b128 v[198:201], v179 offset:21504
	ds_read_b128 v[202:205], v179 offset:22528
	ds_read_b128 v[214:217], v179 offset:23552
	global_load_lds_dwordx4 v[218:219], off
	s_add_i32 m0, s40, 0x2000
	s_add_u32 s44, s14, 0x40000
	v_lshl_add_u64 v[220:221], s[14:15], 0, v[144:145]
	s_addc_u32 s45, s15, 0
	s_add_i32 s40, s52, s61
	global_load_lds_dwordx4 v[220:221], off
	v_lshl_add_u64 v[222:223], s[44:45], 0, v[148:149]
	s_mov_b32 m0, s40
	v_lshl_add_u64 v[224:225], s[16:17], 0, v[146:147]
	global_load_lds_dwordx4 v[222:223], off
	v_lshl_add_u64 v[222:223], s[44:45], 0, v[144:145]
	s_add_i32 m0, s40, 0x2000
	s_nop 0
	global_load_lds_dwordx4 v[222:223], off
	v_lshl_add_u64 v[222:223], s[16:17], 0, v[150:151]
	s_mov_b32 m0, s48
	s_nop 0
	global_load_lds_dwordx4 v[222:223], off
	s_mov_b32 m0, s49
	s_nop 0
	global_load_lds_dwordx4 v[224:225], off
	s_waitcnt vmcnt(8)
	s_waitcnt lgkmcnt(0)
	s_barrier
	s_setprio 1
	s_waitcnt lgkmcnt(0)
	v_mfma_f32_16x16x32_bf16 v[60:63], v[128:131], v[172:175], v[60:63]
	v_mfma_f32_16x16x32_bf16 v[56:59], v[136:139], v[172:175], v[56:59]
	v_mfma_f32_16x16x32_bf16 v[44:47], v[128:131], v[184:187], v[44:47]
	v_mfma_f32_16x16x32_bf16 v[40:43], v[136:139], v[184:187], v[40:43]
	v_mfma_f32_16x16x32_bf16 v[28:31], v[128:131], v[194:197], v[28:31]
	v_mfma_f32_16x16x32_bf16 v[24:27], v[136:139], v[194:197], v[24:27]
	v_mfma_f32_16x16x32_bf16 v[12:15], v[128:131], v[202:205], v[12:15]
	v_mfma_f32_16x16x32_bf16 v[8:11], v[136:139], v[202:205], v[8:11]
	v_mfma_f32_16x16x32_bf16 v[60:63], v[132:135], v[180:183], v[60:63]
	v_mfma_f32_16x16x32_bf16 v[56:59], v[140:143], v[180:183], v[56:59]
	v_mfma_f32_16x16x32_bf16 v[44:47], v[132:135], v[188:191], v[44:47]
	v_mfma_f32_16x16x32_bf16 v[40:43], v[140:143], v[188:191], v[40:43]
	v_mfma_f32_16x16x32_bf16 v[28:31], v[132:135], v[198:201], v[28:31]
	v_mfma_f32_16x16x32_bf16 v[24:27], v[140:143], v[198:201], v[24:27]
	v_mfma_f32_16x16x32_bf16 v[12:15], v[132:135], v[214:217], v[12:15]
	v_mfma_f32_16x16x32_bf16 v[8:11], v[140:143], v[214:217], v[8:11]
	s_setprio 0
	s_setprio 1
	v_mfma_f32_16x16x32_bf16 v[52:55], v[156:159], v[172:175], v[52:55]
	v_mfma_f32_16x16x32_bf16 v[48:51], v[164:167], v[172:175], v[48:51]
	v_mfma_f32_16x16x32_bf16 v[36:39], v[156:159], v[184:187], v[36:39]
	v_mfma_f32_16x16x32_bf16 v[32:35], v[164:167], v[184:187], v[32:35]
	v_mfma_f32_16x16x32_bf16 v[20:23], v[156:159], v[194:197], v[20:23]
	v_mfma_f32_16x16x32_bf16 v[16:19], v[164:167], v[194:197], v[16:19]
	v_mfma_f32_16x16x32_bf16 v[4:7], v[156:159], v[202:205], v[4:7]
	v_mfma_f32_16x16x32_bf16 v[0:3], v[164:167], v[202:205], v[0:3]
	v_mfma_f32_16x16x32_bf16 v[52:55], v[160:163], v[180:183], v[52:55]
	v_mfma_f32_16x16x32_bf16 v[48:51], v[168:171], v[180:183], v[48:51]
	v_mfma_f32_16x16x32_bf16 v[36:39], v[160:163], v[188:191], v[36:39]
	v_mfma_f32_16x16x32_bf16 v[32:35], v[168:171], v[188:191], v[32:35]
	v_mfma_f32_16x16x32_bf16 v[20:23], v[160:163], v[198:201], v[20:23]
	v_mfma_f32_16x16x32_bf16 v[16:19], v[168:171], v[198:201], v[16:19]
	v_mfma_f32_16x16x32_bf16 v[4:7], v[160:163], v[214:217], v[4:7]
	v_mfma_f32_16x16x32_bf16 v[0:3], v[168:171], v[214:217], v[0:3]
	s_setprio 0
	s_barrier
	s_add_i32 s40, 0, 0x18000
	s_add_i32 s44, 0, 0x1c000
	v_add_u32_e32 v140, s40, v178
	v_add_u32_e32 v168, s44, v178
	ds_read_b128 v[128:131], v140
	ds_read_b128 v[132:135], v140 offset:1024
	ds_read_b128 v[136:139], v140 offset:2048
	ds_read_b128 v[140:143], v140 offset:3072
	ds_read_b128 v[156:159], v168
	ds_read_b128 v[160:163], v168 offset:1024
	ds_read_b128 v[164:167], v168 offset:2048
	ds_read_b128 v[168:171], v168 offset:3072
	s_add_u32 s16, s16, 0x40000
	s_addc_u32 s17, s17, 0
	s_mov_b32 m0, s58
	v_lshl_add_u64 v[226:227], s[16:17], 0, v[150:151]
	ds_read_b128 v[172:175], v179 offset:32768
	ds_read_b128 v[180:183], v179 offset:33792
	ds_read_b128 v[184:187], v179 offset:34816
	ds_read_b128 v[188:191], v179 offset:35840
	ds_read_b128 v[194:197], v179 offset:36864
	ds_read_b128 v[198:201], v179 offset:37888
	ds_read_b128 v[202:205], v179 offset:38912
	ds_read_b128 v[214:217], v179 offset:39936
	global_load_lds_dwordx4 v[226:227], off
	v_lshl_add_u64 v[226:227], s[16:17], 0, v[146:147]
	s_mov_b32 m0, s59
	s_nop 0
	global_load_lds_dwordx4 v[226:227], off
	s_waitcnt vmcnt(8)
	s_waitcnt lgkmcnt(0)
	s_barrier
	s_setprio 1
	s_waitcnt lgkmcnt(0)
	v_mfma_f32_16x16x32_bf16 v[124:127], v[128:131], v[172:175], v[124:127]
	v_mfma_f32_16x16x32_bf16 v[120:123], v[136:139], v[172:175], v[120:123]
	v_mfma_f32_16x16x32_bf16 v[108:111], v[128:131], v[184:187], v[108:111]
	v_mfma_f32_16x16x32_bf16 v[104:107], v[136:139], v[184:187], v[104:107]
	v_mfma_f32_16x16x32_bf16 v[92:95], v[128:131], v[194:197], v[92:95]
	v_mfma_f32_16x16x32_bf16 v[88:91], v[136:139], v[194:197], v[88:91]
	v_mfma_f32_16x16x32_bf16 v[76:79], v[128:131], v[202:205], v[76:79]
	v_mfma_f32_16x16x32_bf16 v[72:75], v[136:139], v[202:205], v[72:75]
	v_mfma_f32_16x16x32_bf16 v[124:127], v[132:135], v[180:183], v[124:127]
	v_mfma_f32_16x16x32_bf16 v[120:123], v[140:143], v[180:183], v[120:123]
	v_mfma_f32_16x16x32_bf16 v[108:111], v[132:135], v[188:191], v[108:111]
	v_mfma_f32_16x16x32_bf16 v[104:107], v[140:143], v[188:191], v[104:107]
	v_mfma_f32_16x16x32_bf16 v[92:95], v[132:135], v[198:201], v[92:95]
	v_mfma_f32_16x16x32_bf16 v[88:91], v[140:143], v[198:201], v[88:91]
	v_mfma_f32_16x16x32_bf16 v[76:79], v[132:135], v[214:217], v[76:79]
	v_mfma_f32_16x16x32_bf16 v[72:75], v[140:143], v[214:217], v[72:75]
	s_setprio 0
	s_setprio 1
	v_mfma_f32_16x16x32_bf16 v[116:119], v[156:159], v[172:175], v[116:119]
	v_mfma_f32_16x16x32_bf16 v[112:115], v[164:167], v[172:175], v[112:115]
	v_mfma_f32_16x16x32_bf16 v[100:103], v[156:159], v[184:187], v[100:103]
	v_mfma_f32_16x16x32_bf16 v[96:99], v[164:167], v[184:187], v[96:99]
	v_mfma_f32_16x16x32_bf16 v[84:87], v[156:159], v[194:197], v[84:87]
	v_mfma_f32_16x16x32_bf16 v[80:83], v[164:167], v[194:197], v[80:83]
	v_mfma_f32_16x16x32_bf16 v[68:71], v[156:159], v[202:205], v[68:71]
	v_mfma_f32_16x16x32_bf16 v[64:67], v[164:167], v[202:205], v[64:67]
	v_mfma_f32_16x16x32_bf16 v[116:119], v[160:163], v[180:183], v[116:119]
	v_mfma_f32_16x16x32_bf16 v[112:115], v[168:171], v[180:183], v[112:115]
	v_mfma_f32_16x16x32_bf16 v[100:103], v[160:163], v[188:191], v[100:103]
	v_mfma_f32_16x16x32_bf16 v[96:99], v[168:171], v[188:191], v[96:99]
	v_mfma_f32_16x16x32_bf16 v[84:87], v[160:163], v[198:201], v[84:87]
	v_mfma_f32_16x16x32_bf16 v[80:83], v[168:171], v[198:201], v[80:83]
	v_mfma_f32_16x16x32_bf16 v[68:71], v[160:163], v[214:217], v[68:71]
	v_mfma_f32_16x16x32_bf16 v[64:67], v[168:171], v[214:217], v[64:67]
	s_setprio 0
	s_barrier
	s_add_i32 s16, s40, s61
	v_lshl_add_u64 v[218:219], v[218:219], 0, s[76:77]
	s_mov_b32 m0, s16
	ds_read_b128 v[172:175], v179 offset:49152
	ds_read_b128 v[180:183], v179 offset:50176
	ds_read_b128 v[184:187], v179 offset:51200
	ds_read_b128 v[188:191], v179 offset:52224
	ds_read_b128 v[194:197], v179 offset:53248
	ds_read_b128 v[198:201], v179 offset:54272
	ds_read_b128 v[202:205], v179 offset:55296
	ds_read_b128 v[214:217], v179 offset:56320
	global_load_lds_dwordx4 v[218:219], off
	s_add_i32 m0, s16, 0x2000
	s_add_u32 s14, s14, 0x40080
	v_lshl_add_u64 v[218:219], v[220:221], 0, s[76:77]
	s_addc_u32 s15, s15, 0
	s_add_i32 s16, s44, s61
	global_load_lds_dwordx4 v[218:219], off
	v_lshl_add_u64 v[218:219], s[14:15], 0, v[148:149]
	s_mov_b32 m0, s16
	s_nop 0
	global_load_lds_dwordx4 v[218:219], off
	v_lshl_add_u64 v[218:219], s[14:15], 0, v[144:145]
	s_add_i32 m0, s16, 0x2000
	s_nop 0
	global_load_lds_dwordx4 v[218:219], off
	v_lshl_add_u64 v[218:219], v[222:223], 0, s[76:77]
	s_mov_b32 m0, s26
	s_nop 0
	global_load_lds_dwordx4 v[218:219], off
	v_lshl_add_u64 v[218:219], v[224:225], 0, s[76:77]
	s_mov_b32 m0, s27
	s_nop 0
	global_load_lds_dwordx4 v[218:219], off
	s_waitcnt vmcnt(8)
	s_waitcnt lgkmcnt(0)
	s_barrier
	s_setprio 1
	s_waitcnt lgkmcnt(0)
	v_mfma_f32_16x16x32_bf16 v[60:63], v[128:131], v[172:175], v[60:63]
	v_mfma_f32_16x16x32_bf16 v[56:59], v[136:139], v[172:175], v[56:59]
	v_mfma_f32_16x16x32_bf16 v[44:47], v[128:131], v[184:187], v[44:47]
	v_mfma_f32_16x16x32_bf16 v[40:43], v[136:139], v[184:187], v[40:43]
	v_mfma_f32_16x16x32_bf16 v[28:31], v[128:131], v[194:197], v[28:31]
	v_mfma_f32_16x16x32_bf16 v[24:27], v[136:139], v[194:197], v[24:27]
	v_mfma_f32_16x16x32_bf16 v[12:15], v[128:131], v[202:205], v[12:15]
	v_mfma_f32_16x16x32_bf16 v[8:11], v[136:139], v[202:205], v[8:11]
	v_mfma_f32_16x16x32_bf16 v[60:63], v[132:135], v[180:183], v[60:63]
	v_mfma_f32_16x16x32_bf16 v[56:59], v[140:143], v[180:183], v[56:59]
	v_mfma_f32_16x16x32_bf16 v[44:47], v[132:135], v[188:191], v[44:47]
	v_mfma_f32_16x16x32_bf16 v[40:43], v[140:143], v[188:191], v[40:43]
	v_mfma_f32_16x16x32_bf16 v[28:31], v[132:135], v[198:201], v[28:31]
	v_mfma_f32_16x16x32_bf16 v[24:27], v[140:143], v[198:201], v[24:27]
	v_mfma_f32_16x16x32_bf16 v[12:15], v[132:135], v[214:217], v[12:15]
	v_mfma_f32_16x16x32_bf16 v[8:11], v[140:143], v[214:217], v[8:11]
	s_setprio 0
	s_setprio 1
	v_mfma_f32_16x16x32_bf16 v[52:55], v[156:159], v[172:175], v[52:55]
	v_mfma_f32_16x16x32_bf16 v[48:51], v[164:167], v[172:175], v[48:51]
	v_mfma_f32_16x16x32_bf16 v[36:39], v[156:159], v[184:187], v[36:39]
	v_mfma_f32_16x16x32_bf16 v[32:35], v[164:167], v[184:187], v[32:35]
	v_mfma_f32_16x16x32_bf16 v[20:23], v[156:159], v[194:197], v[20:23]
	v_mfma_f32_16x16x32_bf16 v[16:19], v[164:167], v[194:197], v[16:19]
	v_mfma_f32_16x16x32_bf16 v[4:7], v[156:159], v[202:205], v[4:7]
	v_mfma_f32_16x16x32_bf16 v[0:3], v[164:167], v[202:205], v[0:3]
	v_mfma_f32_16x16x32_bf16 v[52:55], v[160:163], v[180:183], v[52:55]
	v_mfma_f32_16x16x32_bf16 v[48:51], v[168:171], v[180:183], v[48:51]
	v_mfma_f32_16x16x32_bf16 v[36:39], v[160:163], v[188:191], v[36:39]
	v_mfma_f32_16x16x32_bf16 v[32:35], v[168:171], v[188:191], v[32:35]
	s_add_i32 s39, s39, 2
	s_add_u32 s33, s33, 0x100
	s_addc_u32 s38, s38, 0
	s_add_u32 s12, s12, 0x100
	s_addc_u32 s13, s13, 0
	v_mfma_f32_16x16x32_bf16 v[20:23], v[160:163], v[198:201], v[20:23]
	v_mfma_f32_16x16x32_bf16 v[16:19], v[168:171], v[198:201], v[16:19]
	v_mfma_f32_16x16x32_bf16 v[4:7], v[160:163], v[214:217], v[4:7]
	v_mfma_f32_16x16x32_bf16 v[0:3], v[168:171], v[214:217], v[0:3]
	s_setprio 0
	s_barrier
	s_cmp_gt_u32 s39, 13
	s_cbranch_scc0 .LBB0_299
	s_and_b64 vcc, exec, s[80:81]
	s_cbranch_vccz .LBB0_302
	s_barrier

.LBB0_650:
	s_add_u32 s24, s22, 0x100
	s_addc_u32 s25, s23, 0
	s_add_u32 s26, s19, s22
	s_addc_u32 s27, s63, s23
	s_cmp_eq_u32 s64, 4
	s_cselect_b32 s28, 0, s24
	s_cselect_b32 s29, 0, s25
	s_cselect_b32 s26, s13, s26
	s_cselect_b32 s27, s11, s27
	s_add_u32 s28, s2, s28
	s_addc_u32 s29, s3, s29
	s_add_i32 s65, 0, 0x10000
	s_add_i32 s66, 0, 0x14000
	v_add_u32_e32 v140, s65, v166
	v_add_u32_e32 v172, s66, v166
	ds_read_b128 v[128:131], v140
	ds_read_b128 v[132:135], v140 offset:1024
	ds_read_b128 v[136:139], v140 offset:2048
	ds_read_b128 v[140:143], v140 offset:3072
	ds_read_b128 v[144:147], v172
	ds_read_b128 v[148:151], v172 offset:1024
	ds_read_b128 v[168:171], v172 offset:2048
	ds_read_b128 v[172:175], v172 offset:3072
	v_lshl_add_u64 v[218:219], v[162:163], 0, s[22:23]
	s_add_i32 m0, s21, 0xc000
	ds_read_b128 v[176:179], v167
	ds_read_b128 v[180:183], v167 offset:1024
	ds_read_b128 v[184:187], v167 offset:2048
	ds_read_b128 v[188:191], v167 offset:3072
	ds_read_b128 v[194:197], v167 offset:4096
	ds_read_b128 v[198:201], v167 offset:5120
	ds_read_b128 v[202:205], v167 offset:6144
	ds_read_b128 v[214:217], v167 offset:7168
	global_load_lds_dwordx4 v[218:219], off
	v_lshl_add_u64 v[218:219], v[160:161], 0, s[22:23]
	s_add_i32 m0, s21, 0xe000
	s_nop 0
	global_load_lds_dwordx4 v[218:219], off
	s_waitcnt vmcnt(8)
	s_waitcnt lgkmcnt(0)
	s_barrier
	s_setprio 1
	s_waitcnt lgkmcnt(0)
	v_mfma_f32_16x16x32_bf16 v[124:127], v[128:131], v[176:179], v[124:127]
	v_mfma_f32_16x16x32_bf16 v[120:123], v[136:139], v[176:179], v[120:123]
	v_mfma_f32_16x16x32_bf16 v[108:111], v[128:131], v[184:187], v[108:111]
	v_mfma_f32_16x16x32_bf16 v[104:107], v[136:139], v[184:187], v[104:107]
	v_mfma_f32_16x16x32_bf16 v[96:99], v[128:131], v[194:197], v[96:99]
	v_mfma_f32_16x16x32_bf16 v[88:91], v[136:139], v[194:197], v[88:91]
	v_mfma_f32_16x16x32_bf16 v[80:83], v[128:131], v[202:205], v[80:83]
	v_mfma_f32_16x16x32_bf16 v[72:75], v[136:139], v[202:205], v[72:75]
	v_mfma_f32_16x16x32_bf16 v[124:127], v[132:135], v[180:183], v[124:127]
	v_mfma_f32_16x16x32_bf16 v[120:123], v[140:143], v[180:183], v[120:123]
	v_mfma_f32_16x16x32_bf16 v[108:111], v[132:135], v[188:191], v[108:111]
	v_mfma_f32_16x16x32_bf16 v[104:107], v[140:143], v[188:191], v[104:107]
	v_mfma_f32_16x16x32_bf16 v[96:99], v[132:135], v[198:201], v[96:99]
	v_mfma_f32_16x16x32_bf16 v[88:91], v[140:143], v[198:201], v[88:91]
	v_mfma_f32_16x16x32_bf16 v[80:83], v[132:135], v[214:217], v[80:83]
	v_mfma_f32_16x16x32_bf16 v[72:75], v[140:143], v[214:217], v[72:75]
	s_setprio 0
	s_setprio 1
	v_mfma_f32_16x16x32_bf16 v[116:119], v[144:147], v[176:179], v[116:119]
	v_mfma_f32_16x16x32_bf16 v[112:115], v[168:171], v[176:179], v[112:115]
	v_mfma_f32_16x16x32_bf16 v[100:103], v[144:147], v[184:187], v[100:103]
	v_mfma_f32_16x16x32_bf16 v[92:95], v[168:171], v[184:187], v[92:95]
	v_mfma_f32_16x16x32_bf16 v[84:87], v[144:147], v[194:197], v[84:87]
	v_mfma_f32_16x16x32_bf16 v[76:79], v[168:171], v[194:197], v[76:79]
	v_mfma_f32_16x16x32_bf16 v[68:71], v[144:147], v[202:205], v[68:71]
	v_mfma_f32_16x16x32_bf16 v[64:67], v[168:171], v[202:205], v[64:67]
	v_mfma_f32_16x16x32_bf16 v[116:119], v[148:151], v[180:183], v[116:119]
	v_mfma_f32_16x16x32_bf16 v[112:115], v[172:175], v[180:183], v[112:115]
	v_mfma_f32_16x16x32_bf16 v[100:103], v[148:151], v[188:191], v[100:103]
	v_mfma_f32_16x16x32_bf16 v[92:95], v[172:175], v[188:191], v[92:95]
	v_mfma_f32_16x16x32_bf16 v[84:87], v[148:151], v[198:201], v[84:87]
	v_mfma_f32_16x16x32_bf16 v[76:79], v[172:175], v[198:201], v[76:79]
	v_mfma_f32_16x16x32_bf16 v[68:71], v[148:151], v[214:217], v[68:71]
	v_mfma_f32_16x16x32_bf16 v[64:67], v[172:175], v[214:217], v[64:67]
	s_setprio 0
	s_barrier
	s_add_i32 s22, s65, s35
	v_lshl_add_u64 v[218:219], s[26:27], 0, v[156:157]
	s_mov_b32 m0, s22
	ds_read_b128 v[176:179], v167 offset:16384
	ds_read_b128 v[180:183], v167 offset:17408
	ds_read_b128 v[184:187], v167 offset:18432
	ds_read_b128 v[188:191], v167 offset:19456
	ds_read_b128 v[194:197], v167 offset:20480
	ds_read_b128 v[198:201], v167 offset:21504
	ds_read_b128 v[202:205], v167 offset:22528
	ds_read_b128 v[214:217], v167 offset:23552
	global_load_lds_dwordx4 v[218:219], off
	s_add_i32 m0, s22, 0x2000
	s_add_u32 s22, s26, 0x20000
	v_lshl_add_u64 v[220:221], s[26:27], 0, v[152:153]
	s_addc_u32 s23, s27, 0
	s_add_i32 s65, s66, s35
	global_load_lds_dwordx4 v[220:221], off
	v_lshl_add_u64 v[222:223], s[22:23], 0, v[156:157]
	s_mov_b32 m0, s65
	v_lshl_add_u64 v[224:225], s[28:29], 0, v[154:155]
	global_load_lds_dwordx4 v[222:223], off
	v_lshl_add_u64 v[222:223], s[22:23], 0, v[152:153]
	s_add_i32 m0, s65, 0x2000
	s_nop 0
	global_load_lds_dwordx4 v[222:223], off
	v_lshl_add_u64 v[222:223], s[28:29], 0, v[158:159]
	s_mov_b32 m0, s21
	s_nop 0
	global_load_lds_dwordx4 v[222:223], off
	s_mov_b32 m0, s36
	s_nop 0
	global_load_lds_dwordx4 v[224:225], off
	s_waitcnt vmcnt(8)
	s_waitcnt lgkmcnt(0)
	s_barrier
	s_setprio 1
	s_waitcnt lgkmcnt(0)
	v_mfma_f32_16x16x32_bf16 v[60:63], v[128:131], v[176:179], v[60:63]
	v_mfma_f32_16x16x32_bf16 v[56:59], v[136:139], v[176:179], v[56:59]
	v_mfma_f32_16x16x32_bf16 v[48:51], v[128:131], v[184:187], v[48:51]
	v_mfma_f32_16x16x32_bf16 v[40:43], v[136:139], v[184:187], v[40:43]
	v_mfma_f32_16x16x32_bf16 v[32:35], v[128:131], v[194:197], v[32:35]
	v_mfma_f32_16x16x32_bf16 v[24:27], v[136:139], v[194:197], v[24:27]
	v_mfma_f32_16x16x32_bf16 v[16:19], v[128:131], v[202:205], v[16:19]
	v_mfma_f32_16x16x32_bf16 v[8:11], v[136:139], v[202:205], v[8:11]
	v_mfma_f32_16x16x32_bf16 v[60:63], v[132:135], v[180:183], v[60:63]
	v_mfma_f32_16x16x32_bf16 v[56:59], v[140:143], v[180:183], v[56:59]
	v_mfma_f32_16x16x32_bf16 v[48:51], v[132:135], v[188:191], v[48:51]
	v_mfma_f32_16x16x32_bf16 v[40:43], v[140:143], v[188:191], v[40:43]
	v_mfma_f32_16x16x32_bf16 v[32:35], v[132:135], v[198:201], v[32:35]
	v_mfma_f32_16x16x32_bf16 v[24:27], v[140:143], v[198:201], v[24:27]
	v_mfma_f32_16x16x32_bf16 v[16:19], v[132:135], v[214:217], v[16:19]
	v_mfma_f32_16x16x32_bf16 v[8:11], v[140:143], v[214:217], v[8:11]
	s_setprio 0
	s_setprio 1
	v_mfma_f32_16x16x32_bf16 v[52:55], v[144:147], v[176:179], v[52:55]
	v_mfma_f32_16x16x32_bf16 v[44:47], v[168:171], v[176:179], v[44:47]
	v_mfma_f32_16x16x32_bf16 v[36:39], v[144:147], v[184:187], v[36:39]
	v_mfma_f32_16x16x32_bf16 v[28:31], v[168:171], v[184:187], v[28:31]
	v_mfma_f32_16x16x32_bf16 v[20:23], v[144:147], v[194:197], v[20:23]
	v_mfma_f32_16x16x32_bf16 v[12:15], v[168:171], v[194:197], v[12:15]
	v_mfma_f32_16x16x32_bf16 v[4:7], v[144:147], v[202:205], v[4:7]
	v_mfma_f32_16x16x32_bf16 v[0:3], v[168:171], v[202:205], v[0:3]
	v_mfma_f32_16x16x32_bf16 v[52:55], v[148:151], v[180:183], v[52:55]
	v_mfma_f32_16x16x32_bf16 v[44:47], v[172:175], v[180:183], v[44:47]
	v_mfma_f32_16x16x32_bf16 v[36:39], v[148:151], v[188:191], v[36:39]
	v_mfma_f32_16x16x32_bf16 v[28:31], v[172:175], v[188:191], v[28:31]
	v_mfma_f32_16x16x32_bf16 v[20:23], v[148:151], v[198:201], v[20:23]
	v_mfma_f32_16x16x32_bf16 v[12:15], v[172:175], v[198:201], v[12:15]
	v_mfma_f32_16x16x32_bf16 v[4:7], v[148:151], v[214:217], v[4:7]
	v_mfma_f32_16x16x32_bf16 v[0:3], v[172:175], v[214:217], v[0:3]
	s_setprio 0
	s_barrier
	s_add_i32 s65, 0, 0x18000
	s_add_i32 s66, 0, 0x1c000
	v_add_u32_e32 v140, s65, v166
	v_add_u32_e32 v172, s66, v166
	ds_read_b128 v[128:131], v140
	ds_read_b128 v[132:135], v140 offset:1024
	ds_read_b128 v[136:139], v140 offset:2048
	ds_read_b128 v[140:143], v140 offset:3072
	ds_read_b128 v[144:147], v172
	ds_read_b128 v[148:151], v172 offset:1024
	ds_read_b128 v[168:171], v172 offset:2048
	ds_read_b128 v[172:175], v172 offset:3072
	s_add_u32 s22, s28, 0x20000
	s_addc_u32 s23, s29, 0
	s_mov_b32 m0, s37
	v_lshl_add_u64 v[226:227], s[22:23], 0, v[158:159]
	ds_read_b128 v[176:179], v167 offset:32768
	ds_read_b128 v[180:183], v167 offset:33792
	ds_read_b128 v[184:187], v167 offset:34816
	ds_read_b128 v[188:191], v167 offset:35840
	ds_read_b128 v[194:197], v167 offset:36864
	ds_read_b128 v[198:201], v167 offset:37888
	ds_read_b128 v[202:205], v167 offset:38912
	ds_read_b128 v[214:217], v167 offset:39936
	global_load_lds_dwordx4 v[226:227], off
	v_lshl_add_u64 v[226:227], s[22:23], 0, v[154:155]
	s_mov_b32 m0, s38
	s_nop 0
	global_load_lds_dwordx4 v[226:227], off
	s_waitcnt vmcnt(8)
	s_waitcnt lgkmcnt(0)
	s_barrier
	s_setprio 1
	s_waitcnt lgkmcnt(0)
	v_mfma_f32_16x16x32_bf16 v[124:127], v[128:131], v[176:179], v[124:127]
	v_mfma_f32_16x16x32_bf16 v[120:123], v[136:139], v[176:179], v[120:123]
	v_mfma_f32_16x16x32_bf16 v[108:111], v[128:131], v[184:187], v[108:111]
	v_mfma_f32_16x16x32_bf16 v[104:107], v[136:139], v[184:187], v[104:107]
	v_mfma_f32_16x16x32_bf16 v[96:99], v[128:131], v[194:197], v[96:99]
	v_mfma_f32_16x16x32_bf16 v[88:91], v[136:139], v[194:197], v[88:91]
	v_mfma_f32_16x16x32_bf16 v[80:83], v[128:131], v[202:205], v[80:83]
	v_mfma_f32_16x16x32_bf16 v[72:75], v[136:139], v[202:205], v[72:75]
	v_mfma_f32_16x16x32_bf16 v[124:127], v[132:135], v[180:183], v[124:127]
	v_mfma_f32_16x16x32_bf16 v[120:123], v[140:143], v[180:183], v[120:123]
	v_mfma_f32_16x16x32_bf16 v[108:111], v[132:135], v[188:191], v[108:111]
	v_mfma_f32_16x16x32_bf16 v[104:107], v[140:143], v[188:191], v[104:107]
	v_mfma_f32_16x16x32_bf16 v[96:99], v[132:135], v[198:201], v[96:99]
	v_mfma_f32_16x16x32_bf16 v[88:91], v[140:143], v[198:201], v[88:91]
	v_mfma_f32_16x16x32_bf16 v[80:83], v[132:135], v[214:217], v[80:83]
	v_mfma_f32_16x16x32_bf16 v[72:75], v[140:143], v[214:217], v[72:75]
	s_setprio 0
	s_setprio 1
	v_mfma_f32_16x16x32_bf16 v[116:119], v[144:147], v[176:179], v[116:119]
	v_mfma_f32_16x16x32_bf16 v[112:115], v[168:171], v[176:179], v[112:115]
	v_mfma_f32_16x16x32_bf16 v[100:103], v[144:147], v[184:187], v[100:103]
	v_mfma_f32_16x16x32_bf16 v[92:95], v[168:171], v[184:187], v[92:95]
	v_mfma_f32_16x16x32_bf16 v[84:87], v[144:147], v[194:197], v[84:87]
	v_mfma_f32_16x16x32_bf16 v[76:79], v[168:171], v[194:197], v[76:79]
	v_mfma_f32_16x16x32_bf16 v[68:71], v[144:147], v[202:205], v[68:71]
	v_mfma_f32_16x16x32_bf16 v[64:67], v[168:171], v[202:205], v[64:67]
	v_mfma_f32_16x16x32_bf16 v[116:119], v[148:151], v[180:183], v[116:119]
	v_mfma_f32_16x16x32_bf16 v[112:115], v[172:175], v[180:183], v[112:115]
	v_mfma_f32_16x16x32_bf16 v[100:103], v[148:151], v[188:191], v[100:103]
	v_mfma_f32_16x16x32_bf16 v[92:95], v[172:175], v[188:191], v[92:95]
	v_mfma_f32_16x16x32_bf16 v[84:87], v[148:151], v[198:201], v[84:87]
	v_mfma_f32_16x16x32_bf16 v[76:79], v[172:175], v[198:201], v[76:79]
	v_mfma_f32_16x16x32_bf16 v[68:71], v[148:151], v[214:217], v[68:71]
	v_mfma_f32_16x16x32_bf16 v[64:67], v[172:175], v[214:217], v[64:67]
	s_setprio 0
	s_barrier
	s_add_i32 s22, s65, s35
	v_lshl_add_u64 v[218:219], v[218:219], 0, s[76:77]
	s_mov_b32 m0, s22
	ds_read_b128 v[176:179], v167 offset:49152
	ds_read_b128 v[180:183], v167 offset:50176
	ds_read_b128 v[184:187], v167 offset:51200
	ds_read_b128 v[188:191], v167 offset:52224
	ds_read_b128 v[194:197], v167 offset:53248
	ds_read_b128 v[198:201], v167 offset:54272
	ds_read_b128 v[202:205], v167 offset:55296
	ds_read_b128 v[214:217], v167 offset:56320
	global_load_lds_dwordx4 v[218:219], off
	s_add_i32 m0, s22, 0x2000
	s_add_u32 s22, s26, 0x20080
	v_lshl_add_u64 v[218:219], v[220:221], 0, s[76:77]
	s_addc_u32 s23, s27, 0
	s_add_i32 s26, s66, s35
	global_load_lds_dwordx4 v[218:219], off
	v_lshl_add_u64 v[218:219], s[22:23], 0, v[156:157]
	s_mov_b32 m0, s26
	s_nop 0
	global_load_lds_dwordx4 v[218:219], off
	v_lshl_add_u64 v[218:219], s[22:23], 0, v[152:153]
	s_add_i32 m0, s26, 0x2000
	s_nop 0
	global_load_lds_dwordx4 v[218:219], off
	v_lshl_add_u64 v[218:219], v[222:223], 0, s[76:77]
	s_mov_b32 m0, s44
	s_nop 0
	global_load_lds_dwordx4 v[218:219], off
	v_lshl_add_u64 v[218:219], v[224:225], 0, s[76:77]
	s_mov_b32 m0, s45
	s_nop 0
	global_load_lds_dwordx4 v[218:219], off
	s_waitcnt vmcnt(8)
	s_waitcnt lgkmcnt(0)
	s_barrier
	s_setprio 1
	s_waitcnt lgkmcnt(0)
	v_mfma_f32_16x16x32_bf16 v[60:63], v[128:131], v[176:179], v[60:63]
	v_mfma_f32_16x16x32_bf16 v[56:59], v[136:139], v[176:179], v[56:59]
	v_mfma_f32_16x16x32_bf16 v[48:51], v[128:131], v[184:187], v[48:51]
	v_mfma_f32_16x16x32_bf16 v[40:43], v[136:139], v[184:187], v[40:43]
	v_mfma_f32_16x16x32_bf16 v[32:35], v[128:131], v[194:197], v[32:35]
	v_mfma_f32_16x16x32_bf16 v[24:27], v[136:139], v[194:197], v[24:27]
	v_mfma_f32_16x16x32_bf16 v[16:19], v[128:131], v[202:205], v[16:19]
	v_mfma_f32_16x16x32_bf16 v[8:11], v[136:139], v[202:205], v[8:11]
	v_mfma_f32_16x16x32_bf16 v[60:63], v[132:135], v[180:183], v[60:63]
	v_mfma_f32_16x16x32_bf16 v[56:59], v[140:143], v[180:183], v[56:59]
	v_mfma_f32_16x16x32_bf16 v[48:51], v[132:135], v[188:191], v[48:51]
	v_mfma_f32_16x16x32_bf16 v[40:43], v[140:143], v[188:191], v[40:43]
	v_mfma_f32_16x16x32_bf16 v[32:35], v[132:135], v[198:201], v[32:35]
	v_mfma_f32_16x16x32_bf16 v[24:27], v[140:143], v[198:201], v[24:27]
	v_mfma_f32_16x16x32_bf16 v[16:19], v[132:135], v[214:217], v[16:19]
	v_mfma_f32_16x16x32_bf16 v[8:11], v[140:143], v[214:217], v[8:11]
	s_setprio 0
	s_setprio 1
	v_mfma_f32_16x16x32_bf16 v[52:55], v[144:147], v[176:179], v[52:55]
	v_mfma_f32_16x16x32_bf16 v[44:47], v[168:171], v[176:179], v[44:47]
	v_mfma_f32_16x16x32_bf16 v[36:39], v[144:147], v[184:187], v[36:39]
	v_mfma_f32_16x16x32_bf16 v[28:31], v[168:171], v[184:187], v[28:31]
	v_mfma_f32_16x16x32_bf16 v[20:23], v[144:147], v[194:197], v[20:23]
	v_mfma_f32_16x16x32_bf16 v[12:15], v[168:171], v[194:197], v[12:15]
	v_mfma_f32_16x16x32_bf16 v[4:7], v[144:147], v[202:205], v[4:7]
	v_mfma_f32_16x16x32_bf16 v[0:3], v[168:171], v[202:205], v[0:3]
	v_mfma_f32_16x16x32_bf16 v[52:55], v[148:151], v[180:183], v[52:55]
	v_mfma_f32_16x16x32_bf16 v[44:47], v[172:175], v[180:183], v[44:47]
	v_mfma_f32_16x16x32_bf16 v[36:39], v[148:151], v[188:191], v[36:39]
	v_mfma_f32_16x16x32_bf16 v[28:31], v[172:175], v[188:191], v[28:31]
	s_add_i32 s64, s64, 2
	v_mfma_f32_16x16x32_bf16 v[20:23], v[148:151], v[198:201], v[20:23]
	v_mfma_f32_16x16x32_bf16 v[12:15], v[172:175], v[198:201], v[12:15]
	v_mfma_f32_16x16x32_bf16 v[4:7], v[148:151], v[214:217], v[4:7]
	v_mfma_f32_16x16x32_bf16 v[0:3], v[172:175], v[214:217], v[0:3]
	s_setprio 0
	s_barrier
	s_cmp_gt_u32 s64, 5
	s_mov_b64 s[22:23], s[24:25]
	s_cbranch_scc0 .LBB0_650
	s_and_b64 vcc, exec, s[8:9]
	s_cbranch_vccz .LBB0_653
	s_barrier

.LBB0_670:
	s_add_u32 s19, s24, 0xffe00080
	s_addc_u32 s26, s25, -1
	s_add_i32 s63, 0, 0x10000
	s_cmpk_eq_i32 s13, 0x7c
	s_cselect_b32 s29, s15, s26
	s_cselect_b32 s28, s14, s19
	s_cselect_b32 s27, s17, s11
	s_cselect_b32 s26, s16, s9
	s_add_i32 s19, 0, 0x14000
	v_add_u32_e32 v140, s63, v170
	v_add_u32_e32 v172, s19, v170
	ds_read_b128 v[128:131], v140
	ds_read_b128 v[132:135], v140 offset:1024
	ds_read_b128 v[136:139], v140 offset:2048
	ds_read_b128 v[140:143], v140 offset:3072
	ds_read_b128 v[144:147], v172
	ds_read_b128 v[148:151], v172 offset:1024
	ds_read_b128 v[152:155], v172 offset:2048
	ds_read_b128 v[172:175], v172 offset:3072
	v_lshl_add_u64 v[218:219], s[24:25], 0, v[166:167]
	s_add_i32 m0, s23, 0xc000
	ds_read_b128 v[176:179], v171
	ds_read_b128 v[180:183], v171 offset:1024
	ds_read_b128 v[184:187], v171 offset:2048
	ds_read_b128 v[188:191], v171 offset:3072
	ds_read_b128 v[194:197], v171 offset:4096
	ds_read_b128 v[198:201], v171 offset:5120
	ds_read_b128 v[202:205], v171 offset:6144
	ds_read_b128 v[214:217], v171 offset:7168
	global_load_lds_dwordx4 v[218:219], off
	v_lshl_add_u64 v[218:219], s[24:25], 0, v[164:165]
	s_add_i32 m0, s23, 0xe000
	s_nop 0
	global_load_lds_dwordx4 v[218:219], off
	s_waitcnt vmcnt(8)
	s_waitcnt lgkmcnt(0)
	s_barrier
	s_setprio 1
	s_waitcnt lgkmcnt(0)
	v_mfma_f32_16x16x32_bf16 v[124:127], v[128:131], v[176:179], v[124:127]
	v_mfma_f32_16x16x32_bf16 v[120:123], v[136:139], v[176:179], v[120:123]
	v_mfma_f32_16x16x32_bf16 v[108:111], v[128:131], v[184:187], v[108:111]
	v_mfma_f32_16x16x32_bf16 v[104:107], v[136:139], v[184:187], v[104:107]
	v_mfma_f32_16x16x32_bf16 v[96:99], v[128:131], v[194:197], v[96:99]
	v_mfma_f32_16x16x32_bf16 v[88:91], v[136:139], v[194:197], v[88:91]
	v_mfma_f32_16x16x32_bf16 v[80:83], v[128:131], v[202:205], v[80:83]
	v_mfma_f32_16x16x32_bf16 v[72:75], v[136:139], v[202:205], v[72:75]
	v_mfma_f32_16x16x32_bf16 v[124:127], v[132:135], v[180:183], v[124:127]
	v_mfma_f32_16x16x32_bf16 v[120:123], v[140:143], v[180:183], v[120:123]
	v_mfma_f32_16x16x32_bf16 v[108:111], v[132:135], v[188:191], v[108:111]
	v_mfma_f32_16x16x32_bf16 v[104:107], v[140:143], v[188:191], v[104:107]
	v_mfma_f32_16x16x32_bf16 v[96:99], v[132:135], v[198:201], v[96:99]
	v_mfma_f32_16x16x32_bf16 v[88:91], v[140:143], v[198:201], v[88:91]
	v_mfma_f32_16x16x32_bf16 v[80:83], v[132:135], v[214:217], v[80:83]
	v_mfma_f32_16x16x32_bf16 v[72:75], v[140:143], v[214:217], v[72:75]
	s_setprio 0
	s_setprio 1
	v_mfma_f32_16x16x32_bf16 v[116:119], v[144:147], v[176:179], v[116:119]
	v_mfma_f32_16x16x32_bf16 v[112:115], v[152:155], v[176:179], v[112:115]
	v_mfma_f32_16x16x32_bf16 v[100:103], v[144:147], v[184:187], v[100:103]
	v_mfma_f32_16x16x32_bf16 v[92:95], v[152:155], v[184:187], v[92:95]
	v_mfma_f32_16x16x32_bf16 v[84:87], v[144:147], v[194:197], v[84:87]
	v_mfma_f32_16x16x32_bf16 v[76:79], v[152:155], v[194:197], v[76:79]
	v_mfma_f32_16x16x32_bf16 v[68:71], v[144:147], v[202:205], v[68:71]
	v_mfma_f32_16x16x32_bf16 v[64:67], v[152:155], v[202:205], v[64:67]
	v_mfma_f32_16x16x32_bf16 v[116:119], v[148:151], v[180:183], v[116:119]
	v_mfma_f32_16x16x32_bf16 v[112:115], v[172:175], v[180:183], v[112:115]
	v_mfma_f32_16x16x32_bf16 v[100:103], v[148:151], v[188:191], v[100:103]
	v_mfma_f32_16x16x32_bf16 v[92:95], v[172:175], v[188:191], v[92:95]
	v_mfma_f32_16x16x32_bf16 v[84:87], v[148:151], v[198:201], v[84:87]
	v_mfma_f32_16x16x32_bf16 v[76:79], v[172:175], v[198:201], v[76:79]
	v_mfma_f32_16x16x32_bf16 v[68:71], v[148:151], v[214:217], v[68:71]
	v_mfma_f32_16x16x32_bf16 v[64:67], v[172:175], v[214:217], v[64:67]
	s_setprio 0
	s_barrier
	s_add_i32 s63, s63, s36
	v_lshl_add_u64 v[218:219], s[26:27], 0, v[160:161]
	s_mov_b32 m0, s63
	ds_read_b128 v[176:179], v171 offset:16384
	ds_read_b128 v[180:183], v171 offset:17408
	ds_read_b128 v[184:187], v171 offset:18432
	ds_read_b128 v[188:191], v171 offset:19456
	ds_read_b128 v[194:197], v171 offset:20480
	ds_read_b128 v[198:201], v171 offset:21504
	ds_read_b128 v[202:205], v171 offset:22528
	ds_read_b128 v[214:217], v171 offset:23552
	global_load_lds_dwordx4 v[218:219], off
	s_add_i32 m0, s63, 0x2000
	s_add_u32 s64, s26, 0x200000
	v_lshl_add_u64 v[220:221], s[26:27], 0, v[156:157]
	s_addc_u32 s65, s27, 0
	s_add_i32 s19, s19, s36
	global_load_lds_dwordx4 v[220:221], off
	v_lshl_add_u64 v[222:223], s[64:65], 0, v[160:161]
	s_mov_b32 m0, s19
	v_lshl_add_u64 v[224:225], s[28:29], 0, v[158:159]
	global_load_lds_dwordx4 v[222:223], off
	v_lshl_add_u64 v[222:223], s[64:65], 0, v[156:157]
	s_add_i32 m0, s19, 0x2000
	s_nop 0
	global_load_lds_dwordx4 v[222:223], off
	v_lshl_add_u64 v[222:223], s[28:29], 0, v[162:163]
	s_mov_b32 m0, s23
	s_nop 0
	global_load_lds_dwordx4 v[222:223], off
	s_mov_b32 m0, s21
	s_nop 0
	global_load_lds_dwordx4 v[224:225], off
	s_waitcnt vmcnt(8)
	s_waitcnt lgkmcnt(0)
	s_barrier
	s_setprio 1
	s_waitcnt lgkmcnt(0)
	v_mfma_f32_16x16x32_bf16 v[60:63], v[128:131], v[176:179], v[60:63]
	v_mfma_f32_16x16x32_bf16 v[56:59], v[136:139], v[176:179], v[56:59]
	v_mfma_f32_16x16x32_bf16 v[48:51], v[128:131], v[184:187], v[48:51]
	v_mfma_f32_16x16x32_bf16 v[40:43], v[136:139], v[184:187], v[40:43]
	v_mfma_f32_16x16x32_bf16 v[32:35], v[128:131], v[194:197], v[32:35]
	v_mfma_f32_16x16x32_bf16 v[24:27], v[136:139], v[194:197], v[24:27]
	v_mfma_f32_16x16x32_bf16 v[16:19], v[128:131], v[202:205], v[16:19]
	v_mfma_f32_16x16x32_bf16 v[8:11], v[136:139], v[202:205], v[8:11]
	v_mfma_f32_16x16x32_bf16 v[60:63], v[132:135], v[180:183], v[60:63]
	v_mfma_f32_16x16x32_bf16 v[56:59], v[140:143], v[180:183], v[56:59]
	v_mfma_f32_16x16x32_bf16 v[48:51], v[132:135], v[188:191], v[48:51]
	v_mfma_f32_16x16x32_bf16 v[40:43], v[140:143], v[188:191], v[40:43]
	v_mfma_f32_16x16x32_bf16 v[32:35], v[132:135], v[198:201], v[32:35]
	v_mfma_f32_16x16x32_bf16 v[24:27], v[140:143], v[198:201], v[24:27]
	v_mfma_f32_16x16x32_bf16 v[16:19], v[132:135], v[214:217], v[16:19]
	v_mfma_f32_16x16x32_bf16 v[8:11], v[140:143], v[214:217], v[8:11]
	s_setprio 0
	s_setprio 1
	v_mfma_f32_16x16x32_bf16 v[52:55], v[144:147], v[176:179], v[52:55]
	v_mfma_f32_16x16x32_bf16 v[44:47], v[152:155], v[176:179], v[44:47]
	v_mfma_f32_16x16x32_bf16 v[36:39], v[144:147], v[184:187], v[36:39]
	v_mfma_f32_16x16x32_bf16 v[28:31], v[152:155], v[184:187], v[28:31]
	v_mfma_f32_16x16x32_bf16 v[20:23], v[144:147], v[194:197], v[20:23]
	v_mfma_f32_16x16x32_bf16 v[12:15], v[152:155], v[194:197], v[12:15]
	v_mfma_f32_16x16x32_bf16 v[4:7], v[144:147], v[202:205], v[4:7]
	v_mfma_f32_16x16x32_bf16 v[0:3], v[152:155], v[202:205], v[0:3]
	v_mfma_f32_16x16x32_bf16 v[52:55], v[148:151], v[180:183], v[52:55]
	v_mfma_f32_16x16x32_bf16 v[44:47], v[172:175], v[180:183], v[44:47]
	v_mfma_f32_16x16x32_bf16 v[36:39], v[148:151], v[188:191], v[36:39]
	v_mfma_f32_16x16x32_bf16 v[28:31], v[172:175], v[188:191], v[28:31]
	v_mfma_f32_16x16x32_bf16 v[20:23], v[148:151], v[198:201], v[20:23]
	v_mfma_f32_16x16x32_bf16 v[12:15], v[172:175], v[198:201], v[12:15]
	v_mfma_f32_16x16x32_bf16 v[4:7], v[148:151], v[214:217], v[4:7]
	v_mfma_f32_16x16x32_bf16 v[0:3], v[172:175], v[214:217], v[0:3]
	s_setprio 0
	s_barrier
	s_add_i32 s19, 0, 0x18000
	s_add_i32 s63, 0, 0x1c000
	v_add_u32_e32 v140, s19, v170
	v_add_u32_e32 v172, s63, v170
	ds_read_b128 v[128:131], v140
	ds_read_b128 v[132:135], v140 offset:1024
	ds_read_b128 v[136:139], v140 offset:2048
	ds_read_b128 v[140:143], v140 offset:3072
	ds_read_b128 v[144:147], v172
	ds_read_b128 v[148:151], v172 offset:1024
	ds_read_b128 v[152:155], v172 offset:2048
	ds_read_b128 v[172:175], v172 offset:3072
	s_add_u32 s28, s28, 0x200000
	s_addc_u32 s29, s29, 0
	s_mov_b32 m0, s37
	v_lshl_add_u64 v[226:227], s[28:29], 0, v[162:163]
	ds_read_b128 v[176:179], v171 offset:32768
	ds_read_b128 v[180:183], v171 offset:33792
	ds_read_b128 v[184:187], v171 offset:34816
	ds_read_b128 v[188:191], v171 offset:35840
	ds_read_b128 v[194:197], v171 offset:36864
	ds_read_b128 v[198:201], v171 offset:37888
	ds_read_b128 v[202:205], v171 offset:38912
	ds_read_b128 v[214:217], v171 offset:39936
	global_load_lds_dwordx4 v[226:227], off
	v_lshl_add_u64 v[226:227], s[28:29], 0, v[158:159]
	s_mov_b32 m0, s38
	s_nop 0
	global_load_lds_dwordx4 v[226:227], off
	s_waitcnt vmcnt(8)
	s_waitcnt lgkmcnt(0)
	s_barrier
	s_setprio 1
	s_waitcnt lgkmcnt(0)
	v_mfma_f32_16x16x32_bf16 v[124:127], v[128:131], v[176:179], v[124:127]
	v_mfma_f32_16x16x32_bf16 v[120:123], v[136:139], v[176:179], v[120:123]
	v_mfma_f32_16x16x32_bf16 v[108:111], v[128:131], v[184:187], v[108:111]
	v_mfma_f32_16x16x32_bf16 v[104:107], v[136:139], v[184:187], v[104:107]
	v_mfma_f32_16x16x32_bf16 v[96:99], v[128:131], v[194:197], v[96:99]
	v_mfma_f32_16x16x32_bf16 v[88:91], v[136:139], v[194:197], v[88:91]
	v_mfma_f32_16x16x32_bf16 v[80:83], v[128:131], v[202:205], v[80:83]
	v_mfma_f32_16x16x32_bf16 v[72:75], v[136:139], v[202:205], v[72:75]
	v_mfma_f32_16x16x32_bf16 v[124:127], v[132:135], v[180:183], v[124:127]
	v_mfma_f32_16x16x32_bf16 v[120:123], v[140:143], v[180:183], v[120:123]
	v_mfma_f32_16x16x32_bf16 v[108:111], v[132:135], v[188:191], v[108:111]
	v_mfma_f32_16x16x32_bf16 v[104:107], v[140:143], v[188:191], v[104:107]
	v_mfma_f32_16x16x32_bf16 v[96:99], v[132:135], v[198:201], v[96:99]
	v_mfma_f32_16x16x32_bf16 v[88:91], v[140:143], v[198:201], v[88:91]
	v_mfma_f32_16x16x32_bf16 v[80:83], v[132:135], v[214:217], v[80:83]
	v_mfma_f32_16x16x32_bf16 v[72:75], v[140:143], v[214:217], v[72:75]
	s_setprio 0
	s_setprio 1
	v_mfma_f32_16x16x32_bf16 v[116:119], v[144:147], v[176:179], v[116:119]
	v_mfma_f32_16x16x32_bf16 v[112:115], v[152:155], v[176:179], v[112:115]
	v_mfma_f32_16x16x32_bf16 v[100:103], v[144:147], v[184:187], v[100:103]
	v_mfma_f32_16x16x32_bf16 v[92:95], v[152:155], v[184:187], v[92:95]
	v_mfma_f32_16x16x32_bf16 v[84:87], v[144:147], v[194:197], v[84:87]
	v_mfma_f32_16x16x32_bf16 v[76:79], v[152:155], v[194:197], v[76:79]
	v_mfma_f32_16x16x32_bf16 v[68:71], v[144:147], v[202:205], v[68:71]
	v_mfma_f32_16x16x32_bf16 v[64:67], v[152:155], v[202:205], v[64:67]
	v_mfma_f32_16x16x32_bf16 v[116:119], v[148:151], v[180:183], v[116:119]
	v_mfma_f32_16x16x32_bf16 v[112:115], v[172:175], v[180:183], v[112:115]
	v_mfma_f32_16x16x32_bf16 v[100:103], v[148:151], v[188:191], v[100:103]
	v_mfma_f32_16x16x32_bf16 v[92:95], v[172:175], v[188:191], v[92:95]
	v_mfma_f32_16x16x32_bf16 v[84:87], v[148:151], v[198:201], v[84:87]
	v_mfma_f32_16x16x32_bf16 v[76:79], v[172:175], v[198:201], v[76:79]
	v_mfma_f32_16x16x32_bf16 v[68:71], v[148:151], v[214:217], v[68:71]
	v_mfma_f32_16x16x32_bf16 v[64:67], v[172:175], v[214:217], v[64:67]
	s_setprio 0
	s_barrier
	s_add_i32 s19, s19, s36
	v_lshl_add_u64 v[218:219], v[218:219], 0, s[76:77]
	s_mov_b32 m0, s19
	ds_read_b128 v[176:179], v171 offset:49152
	ds_read_b128 v[180:183], v171 offset:50176
	ds_read_b128 v[184:187], v171 offset:51200
	ds_read_b128 v[188:191], v171 offset:52224
	ds_read_b128 v[194:197], v171 offset:53248
	ds_read_b128 v[198:201], v171 offset:54272
	ds_read_b128 v[202:205], v171 offset:55296
	ds_read_b128 v[214:217], v171 offset:56320
	global_load_lds_dwordx4 v[218:219], off
	s_add_i32 m0, s19, 0x2000
	s_add_u32 s26, s26, 0x200080
	v_lshl_add_u64 v[218:219], v[220:221], 0, s[76:77]
	s_addc_u32 s27, s27, 0
	s_add_i32 s19, s63, s36
	global_load_lds_dwordx4 v[218:219], off
	v_lshl_add_u64 v[218:219], s[26:27], 0, v[160:161]
	s_mov_b32 m0, s19
	s_nop 0
	global_load_lds_dwordx4 v[218:219], off
	v_lshl_add_u64 v[218:219], s[26:27], 0, v[156:157]
	s_add_i32 m0, s19, 0x2000
	s_nop 0
	global_load_lds_dwordx4 v[218:219], off
	v_lshl_add_u64 v[218:219], v[222:223], 0, s[76:77]
	s_mov_b32 m0, s44
	s_nop 0
	global_load_lds_dwordx4 v[218:219], off
	v_lshl_add_u64 v[218:219], v[224:225], 0, s[76:77]
	s_mov_b32 m0, s45
	s_nop 0
	global_load_lds_dwordx4 v[218:219], off
	s_waitcnt vmcnt(8)
	s_waitcnt lgkmcnt(0)
	s_barrier
	s_setprio 1
	s_waitcnt lgkmcnt(0)
	v_mfma_f32_16x16x32_bf16 v[60:63], v[128:131], v[176:179], v[60:63]
	v_mfma_f32_16x16x32_bf16 v[56:59], v[136:139], v[176:179], v[56:59]
	v_mfma_f32_16x16x32_bf16 v[48:51], v[128:131], v[184:187], v[48:51]
	v_mfma_f32_16x16x32_bf16 v[40:43], v[136:139], v[184:187], v[40:43]
	v_mfma_f32_16x16x32_bf16 v[32:35], v[128:131], v[194:197], v[32:35]
	v_mfma_f32_16x16x32_bf16 v[24:27], v[136:139], v[194:197], v[24:27]
	v_mfma_f32_16x16x32_bf16 v[16:19], v[128:131], v[202:205], v[16:19]
	v_mfma_f32_16x16x32_bf16 v[8:11], v[136:139], v[202:205], v[8:11]
	v_mfma_f32_16x16x32_bf16 v[60:63], v[132:135], v[180:183], v[60:63]
	v_mfma_f32_16x16x32_bf16 v[56:59], v[140:143], v[180:183], v[56:59]
	v_mfma_f32_16x16x32_bf16 v[48:51], v[132:135], v[188:191], v[48:51]
	v_mfma_f32_16x16x32_bf16 v[40:43], v[140:143], v[188:191], v[40:43]
	v_mfma_f32_16x16x32_bf16 v[32:35], v[132:135], v[198:201], v[32:35]
	v_mfma_f32_16x16x32_bf16 v[24:27], v[140:143], v[198:201], v[24:27]
	v_mfma_f32_16x16x32_bf16 v[16:19], v[132:135], v[214:217], v[16:19]
	v_mfma_f32_16x16x32_bf16 v[8:11], v[140:143], v[214:217], v[8:11]
	s_setprio 0
	s_setprio 1
	v_mfma_f32_16x16x32_bf16 v[52:55], v[144:147], v[176:179], v[52:55]
	v_mfma_f32_16x16x32_bf16 v[44:47], v[152:155], v[176:179], v[44:47]
	v_mfma_f32_16x16x32_bf16 v[36:39], v[144:147], v[184:187], v[36:39]
	v_mfma_f32_16x16x32_bf16 v[28:31], v[152:155], v[184:187], v[28:31]
	v_mfma_f32_16x16x32_bf16 v[20:23], v[144:147], v[194:197], v[20:23]
	v_mfma_f32_16x16x32_bf16 v[12:15], v[152:155], v[194:197], v[12:15]
	v_mfma_f32_16x16x32_bf16 v[4:7], v[144:147], v[202:205], v[4:7]
	v_mfma_f32_16x16x32_bf16 v[0:3], v[152:155], v[202:205], v[0:3]
	v_mfma_f32_16x16x32_bf16 v[52:55], v[148:151], v[180:183], v[52:55]
	v_mfma_f32_16x16x32_bf16 v[44:47], v[172:175], v[180:183], v[44:47]
	v_mfma_f32_16x16x32_bf16 v[36:39], v[148:151], v[188:191], v[36:39]
	v_mfma_f32_16x16x32_bf16 v[28:31], v[172:175], v[188:191], v[28:31]
	s_add_i32 s13, s13, 2
	s_add_u32 s9, s9, 0x100
	s_addc_u32 s11, s11, 0
	s_add_u32 s24, s24, 0x100
	s_addc_u32 s25, s25, 0
	v_mfma_f32_16x16x32_bf16 v[20:23], v[148:151], v[198:201], v[20:23]
	v_mfma_f32_16x16x32_bf16 v[12:15], v[172:175], v[198:201], v[12:15]
	v_mfma_f32_16x16x32_bf16 v[4:7], v[148:151], v[214:217], v[4:7]
	v_mfma_f32_16x16x32_bf16 v[0:3], v[172:175], v[214:217], v[0:3]
	s_setprio 0
	s_barrier
	s_cmpk_gt_u32 s13, 0x7d
	s_cbranch_scc0 .LBB0_670
	s_and_b64 vcc, exec, s[4:5]
	s_cbranch_vccz .LBB0_673
	s_barrier

.LBB0_1021:
	s_add_i32 s64, s63, 2
	s_add_u32 s14, s12, 0x100
	s_addc_u32 s15, s13, 0
	s_add_i32 s65, 0, 0x10000
	s_cmp_eq_u32 s63, 38
	s_cselect_b32 s19, s9, s15
	s_cselect_b32 s18, s8, s14
	s_cselect_b32 s17, s11, s61
	s_cselect_b32 s16, s10, s60
	s_add_i32 s66, 0, 0x14000
	v_add_u32_e32 v140, s65, v222
	v_add_u32_e32 v156, s66, v222
	ds_read_b128 v[128:131], v140
	ds_read_b128 v[132:135], v140 offset:1024
	ds_read_b128 v[136:139], v140 offset:2048
	ds_read_b128 v[140:143], v140 offset:3072
	ds_read_b128 v[144:147], v156
	ds_read_b128 v[148:151], v156 offset:1024
	ds_read_b128 v[152:155], v156 offset:2048
	ds_read_b128 v[156:159], v156 offset:3072
	v_lshl_add_u64 v[228:229], s[12:13], 0, v[204:205]
	s_add_i32 m0, s26, 0xc000
	ds_read_b128 v[160:163], v225
	ds_read_b128 v[164:167], v225 offset:1024
	ds_read_b128 v[168:171], v225 offset:2048
	ds_read_b128 v[172:175], v225 offset:3072
	ds_read_b128 v[176:179], v225 offset:4096
	ds_read_b128 v[180:183], v225 offset:5120
	ds_read_b128 v[184:187], v225 offset:6144
	ds_read_b128 v[188:191], v225 offset:7168
	global_load_lds_dwordx4 v[228:229], off
	v_lshl_add_u64 v[228:229], s[12:13], 0, v[202:203]
	s_add_i32 m0, s26, 0xe000
	s_nop 0
	global_load_lds_dwordx4 v[228:229], off
	s_waitcnt vmcnt(8)
	s_waitcnt lgkmcnt(0)
	s_barrier
	s_setprio 1
	s_waitcnt lgkmcnt(0)
	v_mfma_f32_16x16x32_bf16 v[124:127], v[128:131], v[160:163], v[124:127]
	v_mfma_f32_16x16x32_bf16 v[120:123], v[136:139], v[160:163], v[120:123]
	v_mfma_f32_16x16x32_bf16 v[108:111], v[128:131], v[168:171], v[108:111]
	v_mfma_f32_16x16x32_bf16 v[104:107], v[136:139], v[168:171], v[104:107]
	v_mfma_f32_16x16x32_bf16 v[92:95], v[128:131], v[176:179], v[92:95]
	v_mfma_f32_16x16x32_bf16 v[88:91], v[136:139], v[176:179], v[88:91]
	v_mfma_f32_16x16x32_bf16 v[76:79], v[128:131], v[184:187], v[76:79]
	v_mfma_f32_16x16x32_bf16 v[72:75], v[136:139], v[184:187], v[72:75]
	v_mfma_f32_16x16x32_bf16 v[124:127], v[132:135], v[164:167], v[124:127]
	v_mfma_f32_16x16x32_bf16 v[120:123], v[140:143], v[164:167], v[120:123]
	v_mfma_f32_16x16x32_bf16 v[108:111], v[132:135], v[172:175], v[108:111]
	v_mfma_f32_16x16x32_bf16 v[104:107], v[140:143], v[172:175], v[104:107]
	v_mfma_f32_16x16x32_bf16 v[92:95], v[132:135], v[180:183], v[92:95]
	v_mfma_f32_16x16x32_bf16 v[88:91], v[140:143], v[180:183], v[88:91]
	v_mfma_f32_16x16x32_bf16 v[76:79], v[132:135], v[188:191], v[76:79]
	v_mfma_f32_16x16x32_bf16 v[72:75], v[140:143], v[188:191], v[72:75]
	s_setprio 0
	s_setprio 1
	v_mfma_f32_16x16x32_bf16 v[116:119], v[144:147], v[160:163], v[116:119]
	v_mfma_f32_16x16x32_bf16 v[112:115], v[152:155], v[160:163], v[112:115]
	v_mfma_f32_16x16x32_bf16 v[100:103], v[144:147], v[168:171], v[100:103]
	v_mfma_f32_16x16x32_bf16 v[96:99], v[152:155], v[168:171], v[96:99]
	v_mfma_f32_16x16x32_bf16 v[84:87], v[144:147], v[176:179], v[84:87]
	v_mfma_f32_16x16x32_bf16 v[80:83], v[152:155], v[176:179], v[80:83]
	v_mfma_f32_16x16x32_bf16 v[68:71], v[144:147], v[184:187], v[68:71]
	v_mfma_f32_16x16x32_bf16 v[64:67], v[152:155], v[184:187], v[64:67]
	v_mfma_f32_16x16x32_bf16 v[116:119], v[148:151], v[164:167], v[116:119]
	v_mfma_f32_16x16x32_bf16 v[112:115], v[156:159], v[164:167], v[112:115]
	v_mfma_f32_16x16x32_bf16 v[100:103], v[148:151], v[172:175], v[100:103]
	v_mfma_f32_16x16x32_bf16 v[96:99], v[156:159], v[172:175], v[96:99]
	v_mfma_f32_16x16x32_bf16 v[84:87], v[148:151], v[180:183], v[84:87]
	v_mfma_f32_16x16x32_bf16 v[80:83], v[156:159], v[180:183], v[80:83]
	v_mfma_f32_16x16x32_bf16 v[68:71], v[148:151], v[188:191], v[68:71]
	v_mfma_f32_16x16x32_bf16 v[64:67], v[156:159], v[188:191], v[64:67]
	s_setprio 0
	s_barrier
	s_add_i32 s12, s65, s25
	v_lshl_add_u64 v[228:229], s[16:17], 0, v[196:197]
	s_mov_b32 m0, s12
	ds_read_b128 v[160:163], v225 offset:16384
	ds_read_b128 v[164:167], v225 offset:17408
	ds_read_b128 v[168:171], v225 offset:18432
	ds_read_b128 v[172:175], v225 offset:19456
	ds_read_b128 v[176:179], v225 offset:20480
	ds_read_b128 v[180:183], v225 offset:21504
	ds_read_b128 v[184:187], v225 offset:22528
	ds_read_b128 v[188:191], v225 offset:23552
	global_load_lds_dwordx4 v[228:229], off
	s_add_i32 m0, s12, 0x2000
	s_add_u32 s12, s16, 0xa0000
	v_lshl_add_u64 v[230:231], s[16:17], 0, v[200:201]
	s_addc_u32 s13, s17, 0
	s_add_i32 s65, s66, s25
	global_load_lds_dwordx4 v[230:231], off
	v_lshl_add_u64 v[232:233], s[12:13], 0, v[196:197]
	s_mov_b32 m0, s65
	v_lshl_add_u64 v[234:235], s[18:19], 0, v[198:199]
	global_load_lds_dwordx4 v[232:233], off
	v_lshl_add_u64 v[232:233], s[12:13], 0, v[200:201]
	s_add_i32 m0, s65, 0x2000
	s_nop 0
	global_load_lds_dwordx4 v[232:233], off
	v_lshl_add_u64 v[232:233], s[18:19], 0, v[194:195]
	s_mov_b32 m0, s26
	s_nop 0
	global_load_lds_dwordx4 v[232:233], off
	s_mov_b32 m0, s27
	s_nop 0
	global_load_lds_dwordx4 v[234:235], off
	s_waitcnt vmcnt(8)
	s_waitcnt lgkmcnt(0)
	s_barrier
	s_setprio 1
	s_waitcnt lgkmcnt(0)
	v_mfma_f32_16x16x32_bf16 v[60:63], v[128:131], v[160:163], v[60:63]
	v_mfma_f32_16x16x32_bf16 v[56:59], v[136:139], v[160:163], v[56:59]
	v_mfma_f32_16x16x32_bf16 v[44:47], v[128:131], v[168:171], v[44:47]
	v_mfma_f32_16x16x32_bf16 v[40:43], v[136:139], v[168:171], v[40:43]
	v_mfma_f32_16x16x32_bf16 v[28:31], v[128:131], v[176:179], v[28:31]
	v_mfma_f32_16x16x32_bf16 v[24:27], v[136:139], v[176:179], v[24:27]
	v_mfma_f32_16x16x32_bf16 v[12:15], v[128:131], v[184:187], v[12:15]
	v_mfma_f32_16x16x32_bf16 v[8:11], v[136:139], v[184:187], v[8:11]
	v_mfma_f32_16x16x32_bf16 v[60:63], v[132:135], v[164:167], v[60:63]
	v_mfma_f32_16x16x32_bf16 v[56:59], v[140:143], v[164:167], v[56:59]
	v_mfma_f32_16x16x32_bf16 v[44:47], v[132:135], v[172:175], v[44:47]
	v_mfma_f32_16x16x32_bf16 v[40:43], v[140:143], v[172:175], v[40:43]
	v_mfma_f32_16x16x32_bf16 v[28:31], v[132:135], v[180:183], v[28:31]
	v_mfma_f32_16x16x32_bf16 v[24:27], v[140:143], v[180:183], v[24:27]
	v_mfma_f32_16x16x32_bf16 v[12:15], v[132:135], v[188:191], v[12:15]
	v_mfma_f32_16x16x32_bf16 v[8:11], v[140:143], v[188:191], v[8:11]
	s_setprio 0
	s_setprio 1
	v_mfma_f32_16x16x32_bf16 v[52:55], v[144:147], v[160:163], v[52:55]
	v_mfma_f32_16x16x32_bf16 v[48:51], v[152:155], v[160:163], v[48:51]
	v_mfma_f32_16x16x32_bf16 v[36:39], v[144:147], v[168:171], v[36:39]
	v_mfma_f32_16x16x32_bf16 v[32:35], v[152:155], v[168:171], v[32:35]
	v_mfma_f32_16x16x32_bf16 v[20:23], v[144:147], v[176:179], v[20:23]
	v_mfma_f32_16x16x32_bf16 v[16:19], v[152:155], v[176:179], v[16:19]
	v_mfma_f32_16x16x32_bf16 v[4:7], v[144:147], v[184:187], v[4:7]
	v_mfma_f32_16x16x32_bf16 v[0:3], v[152:155], v[184:187], v[0:3]
	v_mfma_f32_16x16x32_bf16 v[52:55], v[148:151], v[164:167], v[52:55]
	v_mfma_f32_16x16x32_bf16 v[48:51], v[156:159], v[164:167], v[48:51]
	v_mfma_f32_16x16x32_bf16 v[36:39], v[148:151], v[172:175], v[36:39]
	v_mfma_f32_16x16x32_bf16 v[32:35], v[156:159], v[172:175], v[32:35]
	v_mfma_f32_16x16x32_bf16 v[20:23], v[148:151], v[180:183], v[20:23]
	v_mfma_f32_16x16x32_bf16 v[16:19], v[156:159], v[180:183], v[16:19]
	v_mfma_f32_16x16x32_bf16 v[4:7], v[148:151], v[188:191], v[4:7]
	v_mfma_f32_16x16x32_bf16 v[0:3], v[156:159], v[188:191], v[0:3]
	s_setprio 0
	s_barrier
	s_add_i32 s65, 0, 0x18000
	s_add_i32 s66, 0, 0x1c000
	v_add_u32_e32 v140, s65, v222
	v_add_u32_e32 v156, s66, v222
	ds_read_b128 v[128:131], v140
	ds_read_b128 v[132:135], v140 offset:1024
	ds_read_b128 v[136:139], v140 offset:2048
	ds_read_b128 v[140:143], v140 offset:3072
	ds_read_b128 v[144:147], v156
	ds_read_b128 v[148:151], v156 offset:1024
	ds_read_b128 v[152:155], v156 offset:2048
	ds_read_b128 v[156:159], v156 offset:3072
	s_add_u32 s12, s18, 0xa0000
	s_addc_u32 s13, s19, 0
	s_mov_b32 m0, s28
	v_lshl_add_u64 v[236:237], s[12:13], 0, v[194:195]
	ds_read_b128 v[160:163], v225 offset:32768
	ds_read_b128 v[164:167], v225 offset:33792
	ds_read_b128 v[168:171], v225 offset:34816
	ds_read_b128 v[172:175], v225 offset:35840
	ds_read_b128 v[176:179], v225 offset:36864
	ds_read_b128 v[180:183], v225 offset:37888
	ds_read_b128 v[184:187], v225 offset:38912
	ds_read_b128 v[188:191], v225 offset:39936
	global_load_lds_dwordx4 v[236:237], off
	v_lshl_add_u64 v[236:237], s[12:13], 0, v[198:199]
	s_mov_b32 m0, s29
	s_nop 0
	global_load_lds_dwordx4 v[236:237], off
	s_waitcnt vmcnt(8)
	s_waitcnt lgkmcnt(0)
	s_barrier
	s_setprio 1
	s_waitcnt lgkmcnt(0)
	v_mfma_f32_16x16x32_bf16 v[124:127], v[128:131], v[160:163], v[124:127]
	v_mfma_f32_16x16x32_bf16 v[120:123], v[136:139], v[160:163], v[120:123]
	v_mfma_f32_16x16x32_bf16 v[108:111], v[128:131], v[168:171], v[108:111]
	v_mfma_f32_16x16x32_bf16 v[104:107], v[136:139], v[168:171], v[104:107]
	v_mfma_f32_16x16x32_bf16 v[92:95], v[128:131], v[176:179], v[92:95]
	v_mfma_f32_16x16x32_bf16 v[88:91], v[136:139], v[176:179], v[88:91]
	v_mfma_f32_16x16x32_bf16 v[76:79], v[128:131], v[184:187], v[76:79]
	v_mfma_f32_16x16x32_bf16 v[72:75], v[136:139], v[184:187], v[72:75]
	v_mfma_f32_16x16x32_bf16 v[124:127], v[132:135], v[164:167], v[124:127]
	v_mfma_f32_16x16x32_bf16 v[120:123], v[140:143], v[164:167], v[120:123]
	v_mfma_f32_16x16x32_bf16 v[108:111], v[132:135], v[172:175], v[108:111]
	v_mfma_f32_16x16x32_bf16 v[104:107], v[140:143], v[172:175], v[104:107]
	v_mfma_f32_16x16x32_bf16 v[92:95], v[132:135], v[180:183], v[92:95]
	v_mfma_f32_16x16x32_bf16 v[88:91], v[140:143], v[180:183], v[88:91]
	v_mfma_f32_16x16x32_bf16 v[76:79], v[132:135], v[188:191], v[76:79]
	v_mfma_f32_16x16x32_bf16 v[72:75], v[140:143], v[188:191], v[72:75]
	s_setprio 0
	s_setprio 1
	v_mfma_f32_16x16x32_bf16 v[116:119], v[144:147], v[160:163], v[116:119]
	v_mfma_f32_16x16x32_bf16 v[112:115], v[152:155], v[160:163], v[112:115]
	v_mfma_f32_16x16x32_bf16 v[100:103], v[144:147], v[168:171], v[100:103]
	v_mfma_f32_16x16x32_bf16 v[96:99], v[152:155], v[168:171], v[96:99]
	v_mfma_f32_16x16x32_bf16 v[84:87], v[144:147], v[176:179], v[84:87]
	v_mfma_f32_16x16x32_bf16 v[80:83], v[152:155], v[176:179], v[80:83]
	v_mfma_f32_16x16x32_bf16 v[68:71], v[144:147], v[184:187], v[68:71]
	v_mfma_f32_16x16x32_bf16 v[64:67], v[152:155], v[184:187], v[64:67]
	v_mfma_f32_16x16x32_bf16 v[116:119], v[148:151], v[164:167], v[116:119]
	v_mfma_f32_16x16x32_bf16 v[112:115], v[156:159], v[164:167], v[112:115]
	v_mfma_f32_16x16x32_bf16 v[100:103], v[148:151], v[172:175], v[100:103]
	v_mfma_f32_16x16x32_bf16 v[96:99], v[156:159], v[172:175], v[96:99]
	v_mfma_f32_16x16x32_bf16 v[84:87], v[148:151], v[180:183], v[84:87]
	v_mfma_f32_16x16x32_bf16 v[80:83], v[156:159], v[180:183], v[80:83]
	v_mfma_f32_16x16x32_bf16 v[68:71], v[148:151], v[188:191], v[68:71]
	v_mfma_f32_16x16x32_bf16 v[64:67], v[156:159], v[188:191], v[64:67]
	s_setprio 0
	s_barrier
	s_add_i32 s12, s65, s25
	v_lshl_add_u64 v[228:229], v[228:229], 0, s[76:77]
	s_mov_b32 m0, s12
	ds_read_b128 v[160:163], v225 offset:49152
	ds_read_b128 v[164:167], v225 offset:50176
	ds_read_b128 v[168:171], v225 offset:51200
	ds_read_b128 v[172:175], v225 offset:52224
	ds_read_b128 v[176:179], v225 offset:53248
	ds_read_b128 v[180:183], v225 offset:54272
	ds_read_b128 v[184:187], v225 offset:55296
	ds_read_b128 v[188:191], v225 offset:56320
	global_load_lds_dwordx4 v[228:229], off
	s_add_i32 m0, s12, 0x2000
	s_add_u32 s12, s16, 0xa0080
	v_lshl_add_u64 v[228:229], v[230:231], 0, s[76:77]
	s_addc_u32 s13, s17, 0
	s_add_i32 s16, s66, s25
	global_load_lds_dwordx4 v[228:229], off
	v_lshl_add_u64 v[228:229], s[12:13], 0, v[196:197]
	s_mov_b32 m0, s16
	s_nop 0
	global_load_lds_dwordx4 v[228:229], off
	v_lshl_add_u64 v[228:229], s[12:13], 0, v[200:201]
	s_add_i32 m0, s16, 0x2000
	s_nop 0
	global_load_lds_dwordx4 v[228:229], off
	v_lshl_add_u64 v[228:229], v[232:233], 0, s[76:77]
	s_mov_b32 m0, s36
	s_nop 0
	global_load_lds_dwordx4 v[228:229], off
	v_lshl_add_u64 v[228:229], v[234:235], 0, s[76:77]
	s_mov_b32 m0, s37
	s_nop 0
	global_load_lds_dwordx4 v[228:229], off
	s_waitcnt vmcnt(8)
	s_waitcnt lgkmcnt(0)
	s_barrier
	s_setprio 1
	s_waitcnt lgkmcnt(0)
	v_mfma_f32_16x16x32_bf16 v[60:63], v[128:131], v[160:163], v[60:63]
	v_mfma_f32_16x16x32_bf16 v[56:59], v[136:139], v[160:163], v[56:59]
	v_mfma_f32_16x16x32_bf16 v[44:47], v[128:131], v[168:171], v[44:47]
	v_mfma_f32_16x16x32_bf16 v[40:43], v[136:139], v[168:171], v[40:43]
	v_mfma_f32_16x16x32_bf16 v[28:31], v[128:131], v[176:179], v[28:31]
	v_mfma_f32_16x16x32_bf16 v[24:27], v[136:139], v[176:179], v[24:27]
	v_mfma_f32_16x16x32_bf16 v[12:15], v[128:131], v[184:187], v[12:15]
	v_mfma_f32_16x16x32_bf16 v[8:11], v[136:139], v[184:187], v[8:11]
	v_mfma_f32_16x16x32_bf16 v[60:63], v[132:135], v[164:167], v[60:63]
	v_mfma_f32_16x16x32_bf16 v[56:59], v[140:143], v[164:167], v[56:59]
	v_mfma_f32_16x16x32_bf16 v[44:47], v[132:135], v[172:175], v[44:47]
	v_mfma_f32_16x16x32_bf16 v[40:43], v[140:143], v[172:175], v[40:43]
	v_mfma_f32_16x16x32_bf16 v[28:31], v[132:135], v[180:183], v[28:31]
	v_mfma_f32_16x16x32_bf16 v[24:27], v[140:143], v[180:183], v[24:27]
	v_mfma_f32_16x16x32_bf16 v[12:15], v[132:135], v[188:191], v[12:15]
	v_mfma_f32_16x16x32_bf16 v[8:11], v[140:143], v[188:191], v[8:11]
	s_setprio 0
	s_setprio 1
	v_mfma_f32_16x16x32_bf16 v[52:55], v[144:147], v[160:163], v[52:55]
	v_mfma_f32_16x16x32_bf16 v[48:51], v[152:155], v[160:163], v[48:51]
	v_mfma_f32_16x16x32_bf16 v[36:39], v[144:147], v[168:171], v[36:39]
	v_mfma_f32_16x16x32_bf16 v[32:35], v[152:155], v[168:171], v[32:35]
	v_mfma_f32_16x16x32_bf16 v[20:23], v[144:147], v[176:179], v[20:23]
	v_mfma_f32_16x16x32_bf16 v[16:19], v[152:155], v[176:179], v[16:19]
	v_mfma_f32_16x16x32_bf16 v[4:7], v[144:147], v[184:187], v[4:7]
	v_mfma_f32_16x16x32_bf16 v[0:3], v[152:155], v[184:187], v[0:3]
	v_mfma_f32_16x16x32_bf16 v[52:55], v[148:151], v[164:167], v[52:55]
	v_mfma_f32_16x16x32_bf16 v[48:51], v[156:159], v[164:167], v[48:51]
	v_mfma_f32_16x16x32_bf16 v[36:39], v[148:151], v[172:175], v[36:39]
	v_mfma_f32_16x16x32_bf16 v[32:35], v[156:159], v[172:175], v[32:35]
	s_add_u32 s60, s60, 0x100
	s_addc_u32 s61, s61, 0
	s_add_i32 s62, s62, 1
	v_mfma_f32_16x16x32_bf16 v[20:23], v[148:151], v[180:183], v[20:23]
	v_mfma_f32_16x16x32_bf16 v[16:19], v[156:159], v[180:183], v[16:19]
	v_mfma_f32_16x16x32_bf16 v[4:7], v[148:151], v[188:191], v[4:7]
	v_mfma_f32_16x16x32_bf16 v[0:3], v[156:159], v[188:191], v[0:3]
	s_setprio 0
	s_barrier
	s_cmp_gt_u32 s63, 37
	s_mov_b64 s[12:13], s[14:15]
	s_mov_b32 s63, s64
	s_cbranch_scc1 .LBB0_1032

.LBB0_1099:
	s_add_u32 s18, s16, 0xfffc0080
	s_addc_u32 s19, s17, -1
	s_add_i32 s46, 0, 0x10000
	s_cmp_eq_u32 s45, 12
	s_cselect_b32 s21, s5, s19
	s_cselect_b32 s20, s9, s18
	s_cselect_b32 s19, s11, s44
	s_cselect_b32 s18, s42, s43
	s_add_i32 s48, 0, 0x14000
	v_add_u32_e32 v154, s46, v140
	v_add_u32_e32 v170, s48, v140
	ds_read_b128 v[142:145], v154
	ds_read_b128 v[146:149], v154 offset:1024
	ds_read_b128 v[150:153], v154 offset:2048
	ds_read_b128 v[154:157], v154 offset:3072
	ds_read_b128 v[158:161], v170
	ds_read_b128 v[162:165], v170 offset:1024
	ds_read_b128 v[166:169], v170 offset:2048
	ds_read_b128 v[170:173], v170 offset:3072
	v_lshl_add_u64 v[190:191], s[16:17], 0, v[136:137]
	s_add_i32 m0, s28, 0xc000
	ds_read_b128 v[174:177], v141
	ds_read_b128 v[178:181], v141 offset:1024
	ds_read_b128 v[182:185], v141 offset:2048
	ds_read_b128 v[186:189], v141 offset:3072
	ds_read_b128 v[194:197], v141 offset:4096
	ds_read_b128 v[198:201], v141 offset:5120
	ds_read_b128 v[202:205], v141 offset:6144
	ds_read_b128 v[220:223], v141 offset:7168
	global_load_lds_dwordx4 v[190:191], off
	v_lshl_add_u64 v[190:191], s[16:17], 0, v[134:135]
	s_add_i32 m0, s28, 0xe000
	s_nop 0
	global_load_lds_dwordx4 v[190:191], off
	s_waitcnt vmcnt(8)
	s_waitcnt lgkmcnt(0)
	s_barrier
	s_setprio 1
	s_waitcnt lgkmcnt(0)
	v_mfma_f32_16x16x32_bf16 v[124:127], v[142:145], v[174:177], v[124:127]
	v_mfma_f32_16x16x32_bf16 v[120:123], v[150:153], v[174:177], v[120:123]
	v_mfma_f32_16x16x32_bf16 v[116:119], v[142:145], v[182:185], v[116:119]
	v_mfma_f32_16x16x32_bf16 v[112:115], v[150:153], v[182:185], v[112:115]
	v_mfma_f32_16x16x32_bf16 v[100:103], v[142:145], v[194:197], v[100:103]
	v_mfma_f32_16x16x32_bf16 v[96:99], v[150:153], v[194:197], v[96:99]
	v_mfma_f32_16x16x32_bf16 v[84:87], v[142:145], v[202:205], v[84:87]
	v_mfma_f32_16x16x32_bf16 v[80:83], v[150:153], v[202:205], v[80:83]
	v_mfma_f32_16x16x32_bf16 v[124:127], v[146:149], v[178:181], v[124:127]
	v_mfma_f32_16x16x32_bf16 v[120:123], v[154:157], v[178:181], v[120:123]
	v_mfma_f32_16x16x32_bf16 v[116:119], v[146:149], v[186:189], v[116:119]
	v_mfma_f32_16x16x32_bf16 v[112:115], v[154:157], v[186:189], v[112:115]
	v_mfma_f32_16x16x32_bf16 v[100:103], v[146:149], v[198:201], v[100:103]
	v_mfma_f32_16x16x32_bf16 v[96:99], v[154:157], v[198:201], v[96:99]
	v_mfma_f32_16x16x32_bf16 v[84:87], v[146:149], v[220:223], v[84:87]
	v_mfma_f32_16x16x32_bf16 v[80:83], v[154:157], v[220:223], v[80:83]
	s_setprio 0
	s_setprio 1
	v_mfma_f32_16x16x32_bf16 v[108:111], v[158:161], v[174:177], v[108:111]
	v_mfma_f32_16x16x32_bf16 v[104:107], v[166:169], v[174:177], v[104:107]
	v_mfma_f32_16x16x32_bf16 v[92:95], v[158:161], v[182:185], v[92:95]
	v_mfma_f32_16x16x32_bf16 v[88:91], v[166:169], v[182:185], v[88:91]
	v_mfma_f32_16x16x32_bf16 v[76:79], v[158:161], v[194:197], v[76:79]
	v_mfma_f32_16x16x32_bf16 v[72:75], v[166:169], v[194:197], v[72:75]
	v_mfma_f32_16x16x32_bf16 v[68:71], v[158:161], v[202:205], v[68:71]
	v_mfma_f32_16x16x32_bf16 v[64:67], v[166:169], v[202:205], v[64:67]
	v_mfma_f32_16x16x32_bf16 v[108:111], v[162:165], v[178:181], v[108:111]
	v_mfma_f32_16x16x32_bf16 v[104:107], v[170:173], v[178:181], v[104:107]
	v_mfma_f32_16x16x32_bf16 v[92:95], v[162:165], v[186:189], v[92:95]
	v_mfma_f32_16x16x32_bf16 v[88:91], v[170:173], v[186:189], v[88:91]
	v_mfma_f32_16x16x32_bf16 v[76:79], v[162:165], v[198:201], v[76:79]
	v_mfma_f32_16x16x32_bf16 v[72:75], v[170:173], v[198:201], v[72:75]
	v_mfma_f32_16x16x32_bf16 v[68:71], v[162:165], v[220:223], v[68:71]
	v_mfma_f32_16x16x32_bf16 v[64:67], v[170:173], v[220:223], v[64:67]
	s_setprio 0
	s_barrier
	s_add_i32 s46, s46, s27
	v_lshl_add_u64 v[190:191], s[18:19], 0, v[192:193]
	s_mov_b32 m0, s46
	ds_read_b128 v[174:177], v141 offset:16384
	ds_read_b128 v[178:181], v141 offset:17408
	ds_read_b128 v[182:185], v141 offset:18432
	ds_read_b128 v[186:189], v141 offset:19456
	ds_read_b128 v[194:197], v141 offset:20480
	ds_read_b128 v[198:201], v141 offset:21504
	ds_read_b128 v[202:205], v141 offset:22528
	ds_read_b128 v[220:223], v141 offset:23552
	global_load_lds_dwordx4 v[190:191], off
	s_add_i32 m0, s46, 0x2000
	s_add_u32 s46, s18, 0x40000
	v_lshl_add_u64 v[224:225], s[18:19], 0, v[132:133]
	s_addc_u32 s47, s19, 0
	s_add_i32 s48, s48, s27
	global_load_lds_dwordx4 v[224:225], off
	v_lshl_add_u64 v[226:227], s[46:47], 0, v[192:193]
	s_mov_b32 m0, s48
	v_lshl_add_u64 v[228:229], s[20:21], 0, v[130:131]
	global_load_lds_dwordx4 v[226:227], off
	v_lshl_add_u64 v[226:227], s[46:47], 0, v[132:133]
	s_add_i32 m0, s48, 0x2000
	s_nop 0
	global_load_lds_dwordx4 v[226:227], off
	v_lshl_add_u64 v[226:227], s[20:21], 0, v[128:129]
	s_mov_b32 m0, s28
	s_nop 0
	global_load_lds_dwordx4 v[226:227], off
	s_mov_b32 m0, s29
	s_nop 0
	global_load_lds_dwordx4 v[228:229], off
	s_waitcnt vmcnt(8)
	s_waitcnt lgkmcnt(0)
	s_barrier
	s_setprio 1
	s_waitcnt lgkmcnt(0)
	v_mfma_f32_16x16x32_bf16 v[60:63], v[142:145], v[174:177], v[60:63]
	v_mfma_f32_16x16x32_bf16 v[56:59], v[150:153], v[174:177], v[56:59]
	v_mfma_f32_16x16x32_bf16 v[52:55], v[142:145], v[182:185], v[52:55]
	v_mfma_f32_16x16x32_bf16 v[48:51], v[150:153], v[182:185], v[48:51]
	v_mfma_f32_16x16x32_bf16 v[36:39], v[142:145], v[194:197], v[36:39]
	v_mfma_f32_16x16x32_bf16 v[32:35], v[150:153], v[194:197], v[32:35]
	v_mfma_f32_16x16x32_bf16 v[20:23], v[142:145], v[202:205], v[20:23]
	v_mfma_f32_16x16x32_bf16 v[16:19], v[150:153], v[202:205], v[16:19]
	v_mfma_f32_16x16x32_bf16 v[60:63], v[146:149], v[178:181], v[60:63]
	v_mfma_f32_16x16x32_bf16 v[56:59], v[154:157], v[178:181], v[56:59]
	v_mfma_f32_16x16x32_bf16 v[52:55], v[146:149], v[186:189], v[52:55]
	v_mfma_f32_16x16x32_bf16 v[48:51], v[154:157], v[186:189], v[48:51]
	v_mfma_f32_16x16x32_bf16 v[36:39], v[146:149], v[198:201], v[36:39]
	v_mfma_f32_16x16x32_bf16 v[32:35], v[154:157], v[198:201], v[32:35]
	v_mfma_f32_16x16x32_bf16 v[20:23], v[146:149], v[220:223], v[20:23]
	v_mfma_f32_16x16x32_bf16 v[16:19], v[154:157], v[220:223], v[16:19]
	s_setprio 0
	s_setprio 1
	v_mfma_f32_16x16x32_bf16 v[44:47], v[158:161], v[174:177], v[44:47]
	v_mfma_f32_16x16x32_bf16 v[40:43], v[166:169], v[174:177], v[40:43]
	v_mfma_f32_16x16x32_bf16 v[28:31], v[158:161], v[182:185], v[28:31]
	v_mfma_f32_16x16x32_bf16 v[24:27], v[166:169], v[182:185], v[24:27]
	v_mfma_f32_16x16x32_bf16 v[12:15], v[158:161], v[194:197], v[12:15]
	v_mfma_f32_16x16x32_bf16 v[8:11], v[166:169], v[194:197], v[8:11]
	v_mfma_f32_16x16x32_bf16 v[4:7], v[158:161], v[202:205], v[4:7]
	v_mfma_f32_16x16x32_bf16 v[0:3], v[166:169], v[202:205], v[0:3]
	v_mfma_f32_16x16x32_bf16 v[44:47], v[162:165], v[178:181], v[44:47]
	v_mfma_f32_16x16x32_bf16 v[40:43], v[170:173], v[178:181], v[40:43]
	v_mfma_f32_16x16x32_bf16 v[28:31], v[162:165], v[186:189], v[28:31]
	v_mfma_f32_16x16x32_bf16 v[24:27], v[170:173], v[186:189], v[24:27]
	v_mfma_f32_16x16x32_bf16 v[12:15], v[162:165], v[198:201], v[12:15]
	v_mfma_f32_16x16x32_bf16 v[8:11], v[170:173], v[198:201], v[8:11]
	v_mfma_f32_16x16x32_bf16 v[4:7], v[162:165], v[220:223], v[4:7]
	v_mfma_f32_16x16x32_bf16 v[0:3], v[170:173], v[220:223], v[0:3]
	s_setprio 0
	s_barrier
	s_add_i32 s46, 0, 0x18000
	s_add_i32 s47, 0, 0x1c000
	v_add_u32_e32 v154, s46, v140
	v_add_u32_e32 v170, s47, v140
	ds_read_b128 v[142:145], v154
	ds_read_b128 v[146:149], v154 offset:1024
	ds_read_b128 v[150:153], v154 offset:2048
	ds_read_b128 v[154:157], v154 offset:3072
	ds_read_b128 v[158:161], v170
	ds_read_b128 v[162:165], v170 offset:1024
	ds_read_b128 v[166:169], v170 offset:2048
	ds_read_b128 v[170:173], v170 offset:3072
	s_add_u32 s20, s20, 0x40000
	s_addc_u32 s21, s21, 0
	s_mov_b32 m0, s30
	v_lshl_add_u64 v[230:231], s[20:21], 0, v[128:129]
	ds_read_b128 v[174:177], v141 offset:32768
	ds_read_b128 v[178:181], v141 offset:33792
	ds_read_b128 v[182:185], v141 offset:34816
	ds_read_b128 v[186:189], v141 offset:35840
	ds_read_b128 v[194:197], v141 offset:36864
	ds_read_b128 v[198:201], v141 offset:37888
	ds_read_b128 v[202:205], v141 offset:38912
	ds_read_b128 v[220:223], v141 offset:39936
	global_load_lds_dwordx4 v[230:231], off
	v_lshl_add_u64 v[230:231], s[20:21], 0, v[130:131]
	s_mov_b32 m0, s31
	s_nop 0
	global_load_lds_dwordx4 v[230:231], off
	s_waitcnt vmcnt(8)
	s_waitcnt lgkmcnt(0)
	s_barrier
	s_setprio 1
	s_waitcnt lgkmcnt(0)
	v_mfma_f32_16x16x32_bf16 v[124:127], v[142:145], v[174:177], v[124:127]
	v_mfma_f32_16x16x32_bf16 v[120:123], v[150:153], v[174:177], v[120:123]
	v_mfma_f32_16x16x32_bf16 v[116:119], v[142:145], v[182:185], v[116:119]
	v_mfma_f32_16x16x32_bf16 v[112:115], v[150:153], v[182:185], v[112:115]
	v_mfma_f32_16x16x32_bf16 v[100:103], v[142:145], v[194:197], v[100:103]
	v_mfma_f32_16x16x32_bf16 v[96:99], v[150:153], v[194:197], v[96:99]
	v_mfma_f32_16x16x32_bf16 v[84:87], v[142:145], v[202:205], v[84:87]
	v_mfma_f32_16x16x32_bf16 v[80:83], v[150:153], v[202:205], v[80:83]
	v_mfma_f32_16x16x32_bf16 v[124:127], v[146:149], v[178:181], v[124:127]
	v_mfma_f32_16x16x32_bf16 v[120:123], v[154:157], v[178:181], v[120:123]
	v_mfma_f32_16x16x32_bf16 v[116:119], v[146:149], v[186:189], v[116:119]
	v_mfma_f32_16x16x32_bf16 v[112:115], v[154:157], v[186:189], v[112:115]
	v_mfma_f32_16x16x32_bf16 v[100:103], v[146:149], v[198:201], v[100:103]
	v_mfma_f32_16x16x32_bf16 v[96:99], v[154:157], v[198:201], v[96:99]
	v_mfma_f32_16x16x32_bf16 v[84:87], v[146:149], v[220:223], v[84:87]
	v_mfma_f32_16x16x32_bf16 v[80:83], v[154:157], v[220:223], v[80:83]
	s_setprio 0
	s_setprio 1
	v_mfma_f32_16x16x32_bf16 v[108:111], v[158:161], v[174:177], v[108:111]
	v_mfma_f32_16x16x32_bf16 v[104:107], v[166:169], v[174:177], v[104:107]
	v_mfma_f32_16x16x32_bf16 v[92:95], v[158:161], v[182:185], v[92:95]
	v_mfma_f32_16x16x32_bf16 v[88:91], v[166:169], v[182:185], v[88:91]
	v_mfma_f32_16x16x32_bf16 v[76:79], v[158:161], v[194:197], v[76:79]
	v_mfma_f32_16x16x32_bf16 v[72:75], v[166:169], v[194:197], v[72:75]
	v_mfma_f32_16x16x32_bf16 v[68:71], v[158:161], v[202:205], v[68:71]
	v_mfma_f32_16x16x32_bf16 v[64:67], v[166:169], v[202:205], v[64:67]
	v_mfma_f32_16x16x32_bf16 v[108:111], v[162:165], v[178:181], v[108:111]
	v_mfma_f32_16x16x32_bf16 v[104:107], v[170:173], v[178:181], v[104:107]
	v_mfma_f32_16x16x32_bf16 v[92:95], v[162:165], v[186:189], v[92:95]
	v_mfma_f32_16x16x32_bf16 v[88:91], v[170:173], v[186:189], v[88:91]
	v_mfma_f32_16x16x32_bf16 v[76:79], v[162:165], v[198:201], v[76:79]
	v_mfma_f32_16x16x32_bf16 v[72:75], v[170:173], v[198:201], v[72:75]
	v_mfma_f32_16x16x32_bf16 v[68:71], v[162:165], v[220:223], v[68:71]
	v_mfma_f32_16x16x32_bf16 v[64:67], v[170:173], v[220:223], v[64:67]
	s_setprio 0
	s_barrier
	s_add_i32 s20, s46, s27
	v_lshl_add_u64 v[190:191], v[190:191], 0, s[76:77]
	s_mov_b32 m0, s20
	ds_read_b128 v[174:177], v141 offset:49152
	ds_read_b128 v[178:181], v141 offset:50176
	ds_read_b128 v[182:185], v141 offset:51200
	ds_read_b128 v[186:189], v141 offset:52224
	ds_read_b128 v[194:197], v141 offset:53248
	ds_read_b128 v[198:201], v141 offset:54272
	ds_read_b128 v[202:205], v141 offset:55296
	ds_read_b128 v[220:223], v141 offset:56320
	global_load_lds_dwordx4 v[190:191], off
	s_add_i32 m0, s20, 0x2000
	s_add_u32 s18, s18, 0x40080
	v_lshl_add_u64 v[190:191], v[224:225], 0, s[76:77]
	s_addc_u32 s19, s19, 0
	s_add_i32 s20, s47, s27
	global_load_lds_dwordx4 v[190:191], off
	v_lshl_add_u64 v[190:191], s[18:19], 0, v[192:193]
	s_mov_b32 m0, s20
	s_nop 0
	global_load_lds_dwordx4 v[190:191], off
	v_lshl_add_u64 v[190:191], s[18:19], 0, v[132:133]
	s_add_i32 m0, s20, 0x2000
	s_nop 0
	global_load_lds_dwordx4 v[190:191], off
	v_lshl_add_u64 v[190:191], v[226:227], 0, s[76:77]
	s_mov_b32 m0, s36
	s_nop 0
	global_load_lds_dwordx4 v[190:191], off
	v_lshl_add_u64 v[190:191], v[228:229], 0, s[76:77]
	s_mov_b32 m0, s37
	s_nop 0
	global_load_lds_dwordx4 v[190:191], off
	s_waitcnt vmcnt(8)
	s_waitcnt lgkmcnt(0)
	s_barrier
	s_setprio 1
	s_waitcnt lgkmcnt(0)
	v_mfma_f32_16x16x32_bf16 v[60:63], v[142:145], v[174:177], v[60:63]
	v_mfma_f32_16x16x32_bf16 v[56:59], v[150:153], v[174:177], v[56:59]
	v_mfma_f32_16x16x32_bf16 v[52:55], v[142:145], v[182:185], v[52:55]
	v_mfma_f32_16x16x32_bf16 v[48:51], v[150:153], v[182:185], v[48:51]
	v_mfma_f32_16x16x32_bf16 v[36:39], v[142:145], v[194:197], v[36:39]
	v_mfma_f32_16x16x32_bf16 v[32:35], v[150:153], v[194:197], v[32:35]
	v_mfma_f32_16x16x32_bf16 v[20:23], v[142:145], v[202:205], v[20:23]
	v_mfma_f32_16x16x32_bf16 v[16:19], v[150:153], v[202:205], v[16:19]
	v_mfma_f32_16x16x32_bf16 v[60:63], v[146:149], v[178:181], v[60:63]
	v_mfma_f32_16x16x32_bf16 v[56:59], v[154:157], v[178:181], v[56:59]
	v_mfma_f32_16x16x32_bf16 v[52:55], v[146:149], v[186:189], v[52:55]
	v_mfma_f32_16x16x32_bf16 v[48:51], v[154:157], v[186:189], v[48:51]
	v_mfma_f32_16x16x32_bf16 v[36:39], v[146:149], v[198:201], v[36:39]
	v_mfma_f32_16x16x32_bf16 v[32:35], v[154:157], v[198:201], v[32:35]
	v_mfma_f32_16x16x32_bf16 v[20:23], v[146:149], v[220:223], v[20:23]
	v_mfma_f32_16x16x32_bf16 v[16:19], v[154:157], v[220:223], v[16:19]
	s_setprio 0
	s_setprio 1
	v_mfma_f32_16x16x32_bf16 v[44:47], v[158:161], v[174:177], v[44:47]
	v_mfma_f32_16x16x32_bf16 v[40:43], v[166:169], v[174:177], v[40:43]
	v_mfma_f32_16x16x32_bf16 v[28:31], v[158:161], v[182:185], v[28:31]
	v_mfma_f32_16x16x32_bf16 v[24:27], v[166:169], v[182:185], v[24:27]
	v_mfma_f32_16x16x32_bf16 v[12:15], v[158:161], v[194:197], v[12:15]
	v_mfma_f32_16x16x32_bf16 v[8:11], v[166:169], v[194:197], v[8:11]
	v_mfma_f32_16x16x32_bf16 v[4:7], v[158:161], v[202:205], v[4:7]
	v_mfma_f32_16x16x32_bf16 v[0:3], v[166:169], v[202:205], v[0:3]
	v_mfma_f32_16x16x32_bf16 v[44:47], v[162:165], v[178:181], v[44:47]
	v_mfma_f32_16x16x32_bf16 v[40:43], v[170:173], v[178:181], v[40:43]
	v_mfma_f32_16x16x32_bf16 v[28:31], v[162:165], v[186:189], v[28:31]
	v_mfma_f32_16x16x32_bf16 v[24:27], v[170:173], v[186:189], v[24:27]
	s_add_i32 s45, s45, 2
	s_add_u32 s43, s43, 0x100
	s_addc_u32 s44, s44, 0
	s_add_u32 s16, s16, 0x100
	s_addc_u32 s17, s17, 0
	v_mfma_f32_16x16x32_bf16 v[12:15], v[162:165], v[198:201], v[12:15]
	v_mfma_f32_16x16x32_bf16 v[8:11], v[170:173], v[198:201], v[8:11]
	v_mfma_f32_16x16x32_bf16 v[4:7], v[162:165], v[220:223], v[4:7]
	v_mfma_f32_16x16x32_bf16 v[0:3], v[170:173], v[220:223], v[0:3]
	s_setprio 0
	s_barrier
	s_cmp_gt_u32 s45, 13
	s_cbranch_scc0 .LBB0_1099
	s_and_b64 vcc, exec, s[2:3]
	s_cbranch_vccz .LBB0_1102
	s_barrier
